# v087 + dead zero-inits before v_cvt_pk_fp8 lo/hi pairs removed (234) + redundant canonicalising v_max pairs merged (49), mostly in the attention loops
# speedup vs baseline: 1.0030x; 1.0030x over previous
.LBB0_430:
	s_nop 15
	s_nop 15
	v_pk_mul_f32 v[4:5], v[170:171], s[22:23] op_sel_hi:[1,0]
	v_pk_mul_f32 v[12:13], v[174:175], s[22:23] op_sel_hi:[1,0]
	v_cvt_pk_fp8_f32 v2, v4, v5
	v_cvt_pk_fp8_f32 v3, v12, v13
	v_pk_mul_f32 v[4:5], v[172:173], s[22:23] op_sel_hi:[1,0]
	v_pk_mul_f32 v[12:13], v[176:177], s[22:23] op_sel_hi:[1,0]
	v_cvt_pk_fp8_f32 v2, v4, v5 op_sel:[0,0,1]
	v_cvt_pk_fp8_f32 v3, v12, v13 op_sel:[0,0,1]
	v_pk_mul_f32 v[12:13], v[154:155], s[22:23] op_sel_hi:[1,0]
	v_pk_mul_f32 v[14:15], v[158:159], s[22:23] op_sel_hi:[1,0]
	v_cvt_pk_fp8_f32 v4, v12, v13
	v_cvt_pk_fp8_f32 v5, v14, v15
	v_pk_mul_f32 v[12:13], v[156:157], s[22:23] op_sel_hi:[1,0]
	v_lshl_add_u32 v6, s34, 8, v214
	v_cvt_pk_fp8_f32 v4, v12, v13 op_sel:[0,0,1]
	v_pk_mul_f32 v[12:13], v[160:161], s[22:23] op_sel_hi:[1,0]
	v_lshl_add_u32 v8, s67, 7, v215
	v_cvt_pk_fp8_f32 v5, v12, v13 op_sel:[0,0,1]
	v_ashrrev_i32_e32 v9, 31, v8
	v_ashrrev_i32_e32 v7, 31, v6
	v_lshl_add_u64 v[10:11], s[8:9], 0, v[8:9]
	v_lshlrev_b64 v[12:13], 11, v[6:7]
	v_permlane16_swap_b32_e32 v2, v4
	v_permlane16_swap_b32_e32 v3, v5
	v_lshl_add_u64 v[14:15], v[10:11], 0, v[12:13]
	global_store_dwordx4 v[14:15], v[2:5], off
	v_pk_mul_f32 v[14:15], v[142:143], s[22:23] op_sel_hi:[1,0]
	v_pk_mul_f32 v[16:17], v[134:135], s[22:23] op_sel_hi:[1,0]
	v_pk_mul_f32 v[4:5], v[138:139], s[22:23] op_sel_hi:[1,0]
	v_cvt_pk_fp8_f32 v2, v4, v5
	v_cvt_pk_fp8_f32 v3, v14, v15
	v_pk_mul_f32 v[4:5], v[140:141], s[22:23] op_sel_hi:[1,0]
	v_pk_mul_f32 v[14:15], v[144:145], s[22:23] op_sel_hi:[1,0]
	v_cvt_pk_fp8_f32 v2, v4, v5 op_sel:[0,0,1]
	v_cvt_pk_fp8_f32 v3, v14, v15 op_sel:[0,0,1]
	v_pk_mul_f32 v[14:15], v[130:131], s[22:23] op_sel_hi:[1,0]
	v_cvt_pk_fp8_f32 v4, v14, v15
	v_cvt_pk_fp8_f32 v5, v16, v17
	v_pk_mul_f32 v[14:15], v[132:133], s[22:23] op_sel_hi:[1,0]
	v_or_b32_e32 v6, 32, v6
	v_cvt_pk_fp8_f32 v4, v14, v15 op_sel:[0,0,1]
	v_pk_mul_f32 v[14:15], v[136:137], s[22:23] op_sel_hi:[1,0]
	v_ashrrev_i32_e32 v7, 31, v6
	v_cvt_pk_fp8_f32 v5, v14, v15 op_sel:[0,0,1]
	v_lshlrev_b64 v[6:7], 11, v[6:7]
	v_permlane16_swap_b32_e32 v2, v4
	v_permlane16_swap_b32_e32 v3, v5
	v_lshl_add_u64 v[14:15], v[10:11], 0, v[6:7]
	global_store_dwordx4 v[14:15], v[2:5], off
	v_pk_mul_f32 v[14:15], v[190:191], s[22:23] op_sel_hi:[1,0]
	v_pk_mul_f32 v[16:17], v[182:183], s[22:23] op_sel_hi:[1,0]
	v_pk_mul_f32 v[4:5], v[186:187], s[22:23] op_sel_hi:[1,0]
	v_cvt_pk_fp8_f32 v2, v4, v5
	v_cvt_pk_fp8_f32 v3, v14, v15
	v_pk_mul_f32 v[4:5], v[188:189], s[22:23] op_sel_hi:[1,0]
	v_pk_mul_f32 v[14:15], v[192:193], s[22:23] op_sel_hi:[1,0]
	v_cvt_pk_fp8_f32 v2, v4, v5 op_sel:[0,0,1]
	v_cvt_pk_fp8_f32 v3, v14, v15 op_sel:[0,0,1]
	v_pk_mul_f32 v[14:15], v[178:179], s[22:23] op_sel_hi:[1,0]
	v_cvt_pk_fp8_f32 v4, v14, v15
	v_cvt_pk_fp8_f32 v5, v16, v17
	v_pk_mul_f32 v[14:15], v[180:181], s[22:23] op_sel_hi:[1,0]
	v_pk_mul_f32 v[18:19], v[150:151], s[22:23] op_sel_hi:[1,0]
	v_cvt_pk_fp8_f32 v4, v14, v15 op_sel:[0,0,1]
	v_pk_mul_f32 v[14:15], v[184:185], s[22:23] op_sel_hi:[1,0]
	v_lshl_add_u64 v[8:9], s[10:11], 0, v[8:9]
	v_cvt_pk_fp8_f32 v5, v14, v15 op_sel:[0,0,1]
	v_lshl_add_u64 v[14:15], v[12:13], 0, s[24:25]
	v_permlane16_swap_b32_e32 v2, v4
	v_permlane16_swap_b32_e32 v3, v5
	v_lshl_add_u64 v[16:17], v[10:11], 0, v[14:15]
	global_store_dwordx4 v[16:17], v[2:5], off
	v_pk_mul_f32 v[16:17], v[166:167], s[22:23] op_sel_hi:[1,0]
	v_lshl_add_u64 v[6:7], v[8:9], 0, v[6:7]
	v_pk_mul_f32 v[4:5], v[162:163], s[22:23] op_sel_hi:[1,0]
	v_cvt_pk_fp8_f32 v2, v4, v5
	v_cvt_pk_fp8_f32 v3, v16, v17
	v_pk_mul_f32 v[4:5], v[164:165], s[22:23] op_sel_hi:[1,0]
	v_pk_mul_f32 v[16:17], v[168:169], s[22:23] op_sel_hi:[1,0]
	v_cvt_pk_fp8_f32 v2, v4, v5 op_sel:[0,0,1]
	v_cvt_pk_fp8_f32 v3, v16, v17 op_sel:[0,0,1]
	v_pk_mul_f32 v[16:17], v[146:147], s[22:23] op_sel_hi:[1,0]
	v_cvt_pk_fp8_f32 v4, v16, v17
	v_cvt_pk_fp8_f32 v5, v18, v19
	v_pk_mul_f32 v[16:17], v[148:149], s[22:23] op_sel_hi:[1,0]
	v_pk_mul_f32 v[18:19], v[90:91], s[22:23] op_sel_hi:[1,0]
	v_cvt_pk_fp8_f32 v4, v16, v17 op_sel:[0,0,1]
	v_pk_mul_f32 v[16:17], v[152:153], s[22:23] op_sel_hi:[1,0]
	s_andn2_b64 vcc, exec, s[2:3]
	v_cvt_pk_fp8_f32 v5, v16, v17 op_sel:[0,0,1]
	v_lshl_add_u64 v[16:17], v[12:13], 0, s[26:27]
	v_permlane16_swap_b32_e32 v2, v4
	v_permlane16_swap_b32_e32 v3, v5
	v_lshl_add_u64 v[10:11], v[10:11], 0, v[16:17]
	global_store_dwordx4 v[10:11], v[2:5], off
	v_pk_mul_f32 v[10:11], v[102:103], s[22:23] op_sel_hi:[1,0]
	s_nop 0
	v_pk_mul_f32 v[4:5], v[98:99], s[22:23] op_sel_hi:[1,0]
	v_cvt_pk_fp8_f32 v2, v4, v5
	v_cvt_pk_fp8_f32 v3, v10, v11
	v_pk_mul_f32 v[4:5], v[100:101], s[22:23] op_sel_hi:[1,0]
	v_pk_mul_f32 v[10:11], v[104:105], s[22:23] op_sel_hi:[1,0]
	v_cvt_pk_fp8_f32 v2, v4, v5 op_sel:[0,0,1]
	v_cvt_pk_fp8_f32 v3, v10, v11 op_sel:[0,0,1]
	v_pk_mul_f32 v[10:11], v[86:87], s[22:23] op_sel_hi:[1,0]
	v_cvt_pk_fp8_f32 v4, v10, v11
	v_cvt_pk_fp8_f32 v5, v18, v19
	v_pk_mul_f32 v[10:11], v[88:89], s[22:23] op_sel_hi:[1,0]
	s_nop 0
	v_cvt_pk_fp8_f32 v4, v10, v11 op_sel:[0,0,1]
	v_pk_mul_f32 v[10:11], v[92:93], s[22:23] op_sel_hi:[1,0]
	s_nop 0
	v_permlane16_swap_b32_e32 v2, v4
	v_cvt_pk_fp8_f32 v5, v10, v11 op_sel:[0,0,1]
	v_lshl_add_u64 v[10:11], v[8:9], 0, v[12:13]
	v_pk_mul_f32 v[12:13], v[66:67], s[22:23] op_sel_hi:[1,0]
	v_permlane16_swap_b32_e32 v3, v5
	global_store_dwordx4 v[10:11], v[2:5], off
	v_pk_mul_f32 v[10:11], v[82:83], s[22:23] op_sel_hi:[1,0]
	s_nop 0
	v_pk_mul_f32 v[4:5], v[78:79], s[22:23] op_sel_hi:[1,0]
	v_cvt_pk_fp8_f32 v2, v4, v5
	v_cvt_pk_fp8_f32 v3, v10, v11
	v_pk_mul_f32 v[4:5], v[80:81], s[22:23] op_sel_hi:[1,0]
	v_pk_mul_f32 v[10:11], v[84:85], s[22:23] op_sel_hi:[1,0]
	v_cvt_pk_fp8_f32 v2, v4, v5 op_sel:[0,0,1]
	v_cvt_pk_fp8_f32 v3, v10, v11 op_sel:[0,0,1]
	v_pk_mul_f32 v[10:11], v[74:75], s[22:23] op_sel_hi:[1,0]
	v_cvt_pk_fp8_f32 v4, v10, v11
	v_cvt_pk_fp8_f32 v5, v12, v13
	v_pk_mul_f32 v[10:11], v[76:77], s[22:23] op_sel_hi:[1,0]
	s_nop 0
	v_cvt_pk_fp8_f32 v4, v10, v11 op_sel:[0,0,1]
	v_pk_mul_f32 v[10:11], v[68:69], s[22:23] op_sel_hi:[1,0]
	s_nop 0
	v_permlane16_swap_b32_e32 v2, v4
	v_cvt_pk_fp8_f32 v5, v10, v11 op_sel:[0,0,1]
	v_pk_mul_f32 v[10:11], v[118:119], s[22:23] op_sel_hi:[1,0]
	s_nop 0
	v_permlane16_swap_b32_e32 v3, v5
	global_store_dwordx4 v[6:7], v[2:5], off
	v_pk_mul_f32 v[6:7], v[126:127], s[22:23] op_sel_hi:[1,0]
	s_nop 0
	v_pk_mul_f32 v[4:5], v[122:123], s[22:23] op_sel_hi:[1,0]
	v_cvt_pk_fp8_f32 v2, v4, v5
	v_cvt_pk_fp8_f32 v3, v6, v7
	v_pk_mul_f32 v[4:5], v[124:125], s[22:23] op_sel_hi:[1,0]
	v_pk_mul_f32 v[6:7], v[128:129], s[22:23] op_sel_hi:[1,0]
	v_cvt_pk_fp8_f32 v2, v4, v5 op_sel:[0,0,1]
	v_cvt_pk_fp8_f32 v3, v6, v7 op_sel:[0,0,1]
	v_pk_mul_f32 v[6:7], v[114:115], s[22:23] op_sel_hi:[1,0]
	v_cvt_pk_fp8_f32 v4, v6, v7
	v_cvt_pk_fp8_f32 v5, v10, v11
	v_pk_mul_f32 v[6:7], v[116:117], s[22:23] op_sel_hi:[1,0]
	v_pk_mul_f32 v[10:11], v[70:71], s[22:23] op_sel_hi:[1,0]
	v_cvt_pk_fp8_f32 v4, v6, v7 op_sel:[0,0,1]
	v_pk_mul_f32 v[6:7], v[120:121], s[22:23] op_sel_hi:[1,0]
	s_nop 0
	v_permlane16_swap_b32_e32 v2, v4
	v_cvt_pk_fp8_f32 v5, v6, v7 op_sel:[0,0,1]
	v_lshl_add_u64 v[6:7], v[8:9], 0, v[14:15]
	s_nop 0
	v_permlane16_swap_b32_e32 v3, v5
	global_store_dwordx4 v[6:7], v[2:5], off
	v_pk_mul_f32 v[6:7], v[110:111], s[22:23] op_sel_hi:[1,0]
	s_nop 0
	v_pk_mul_f32 v[4:5], v[106:107], s[22:23] op_sel_hi:[1,0]
	v_cvt_pk_fp8_f32 v2, v4, v5
	v_cvt_pk_fp8_f32 v3, v6, v7
	v_pk_mul_f32 v[4:5], v[108:109], s[22:23] op_sel_hi:[1,0]
	v_pk_mul_f32 v[6:7], v[112:113], s[22:23] op_sel_hi:[1,0]
	v_cvt_pk_fp8_f32 v2, v4, v5 op_sel:[0,0,1]
	v_cvt_pk_fp8_f32 v3, v6, v7 op_sel:[0,0,1]
	v_pk_mul_f32 v[6:7], v[94:95], s[22:23] op_sel_hi:[1,0]
	v_cvt_pk_fp8_f32 v4, v6, v7
	v_cvt_pk_fp8_f32 v5, v10, v11
	v_pk_mul_f32 v[6:7], v[96:97], s[22:23] op_sel_hi:[1,0]
	s_nop 0
	v_cvt_pk_fp8_f32 v4, v6, v7 op_sel:[0,0,1]
	v_pk_mul_f32 v[6:7], v[72:73], s[22:23] op_sel_hi:[1,0]
	s_nop 0
	v_permlane16_swap_b32_e32 v2, v4
	v_cvt_pk_fp8_f32 v5, v6, v7 op_sel:[0,0,1]
	v_lshl_add_u64 v[6:7], v[8:9], 0, v[16:17]
	s_nop 0
	v_permlane16_swap_b32_e32 v3, v5
	global_store_dwordx4 v[6:7], v[2:5], off
	s_cbranch_vccnz .LBB0_433
	s_andn2_b64 vcc, exec, s[0:1]
	s_cbranch_vccnz .LBB0_409
	s_barrier
	s_branch .LBB0_409

.LBB0_507:
	s_add_i32 s27, s55, 0x8000
	s_mov_b32 m0, s27
	s_add_i32 s26, s37, s57
	global_load_lds_dwordx4 v[186:187], off
	s_mov_b32 m0, s26
	s_nop 0
	global_load_lds_dwordx4 v[182:183], off
	ds_read_b128 v[102:105], v213 offset:49152
	ds_read_b128 v[106:109], v214 offset:49152
	ds_read_b128 v[130:133], v215 offset:49152
	ds_read_b128 v[134:137], v216 offset:49152
	v_add_u32_e32 v228, v226, v219
	v_add_u32_e32 v229, v226, v221
	s_waitcnt lgkmcnt(0)
	v_mfma_f32_32x32x64_f8f6f4 v[86:101], v[102:109], v[146:153], 0
	ds_read_b128 v[102:105], v217 offset:49152
	ds_read_b128 v[106:109], v218 offset:49152
	v_exp_f32_e32 v66, v66
	v_exp_f32_e32 v67, v67
	v_exp_f32_e32 v68, v68
	v_mfma_f32_32x32x64_f8f6f4 v[114:129], v[130:137], v[146:153], 0
	ds_read_b128 v[234:237], v211 offset:49152
	ds_read_b128 v[238:241], v212 offset:49152
	v_exp_f32_e32 v69, v69
	v_exp_f32_e32 v70, v70
	v_exp_f32_e32 v71, v71
	s_waitcnt lgkmcnt(0)
	v_mfma_f32_32x32x64_f8f6f4 v[86:101], v[102:109], v[154:161], v[86:101]
	ds_read_b128 v[102:105], v228
	ds_read_b128 v[106:109], v229
	v_exp_f32_e32 v72, v72
	v_exp_f32_e32 v73, v73
	v_exp_f32_e32 v74, v74
	v_add_u32_e32 v231, v227, v219
	v_mfma_f32_32x32x64_f8f6f4 v[114:129], v[234:241], v[154:161], v[114:129]
	v_add_u32_e32 v232, v227, v221
	ds_read_b128 v[234:237], v231
	ds_read_b128 v[238:241], v232
	v_exp_f32_e32 v75, v75
	v_exp_f32_e32 v76, v76
	v_exp_f32_e32 v77, v77
	s_waitcnt lgkmcnt(0)
	v_mfma_f32_32x32x64_f8f6f4 v[86:101], v[102:109], v[162:169], v[86:101]
	v_exp_f32_e32 v78, v78
	v_exp_f32_e32 v79, v79
	v_mfma_f32_32x32x64_f8f6f4 v[114:129], v[234:241], v[162:169], v[114:129]
	ds_read_b64_tr_b8 v[102:103], v208 offset:0
	ds_read_b64_tr_b8 v[104:105], v208 offset:0x800
	ds_read_b64_tr_b8 v[106:107], v208 offset:0x1000
	ds_read_b64_tr_b8 v[108:109], v208 offset:0x1800
	v_cvt_pk_fp8_f32 v130, v82, v83
	v_cvt_pk_fp8_f32 v131, v190, v191
	v_cvt_pk_fp8_f32 v132, v144, v145
	v_cvt_pk_fp8_f32 v134, v66, v67
	v_cvt_pk_fp8_f32 v135, v70, v71
	v_exp_f32_e32 v80, v80
	v_exp_f32_e32 v81, v81
	v_cvt_pk_fp8_f32 v136, v74, v75
	v_cvt_pk_fp8_f32 v133, v142, v143
	v_cvt_pk_fp8_f32 v137, v78, v79
	ds_read_b64_tr_b8 v[236:237], v210 offset:0
	ds_read_b64_tr_b8 v[238:239], v210 offset:0x800
	ds_read_b64_tr_b8 v[240:241], v210 offset:0x1000
	ds_read_b64_tr_b8 v[242:243], v210 offset:0x1800
	v_cvt_pk_fp8_f32 v130, v84, v85 op_sel:[0,0,1]
	v_cvt_pk_fp8_f32 v131, v188, v189 op_sel:[0,0,1]
	v_cvt_pk_fp8_f32 v134, v68, v69 op_sel:[0,0,1]
	v_cvt_pk_fp8_f32 v135, v72, v73 op_sel:[0,0,1]
	v_cvt_pk_fp8_f32 v132, v138, v139 op_sel:[0,0,1]
	v_cvt_pk_fp8_f32 v136, v76, v77 op_sel:[0,0,1]
	v_cvt_pk_fp8_f32 v133, v140, v141 op_sel:[0,0,1]
	v_cvt_pk_fp8_f32 v137, v80, v81 op_sel:[0,0,1]
	s_waitcnt lgkmcnt(4)
	s_mov_b32 m0, s55
	v_mfma_f32_32x32x64_f8f6f4 v[2:17], v[130:137], v[102:109], v[2:17]
	ds_read_b64_tr_b8 v[244:245], v209 offset:0
	ds_read_b64_tr_b8 v[246:247], v209 offset:0x800
	ds_read_b64_tr_b8 v[248:249], v209 offset:0x1000
	ds_read_b64_tr_b8 v[250:251], v209 offset:0x1800
	s_waitcnt lgkmcnt(4)
	s_nop 0
	v_max_f32_e32 v102, v86, v87
	v_max3_f32 v102, v102, v88, v89
	v_max3_f32 v102, v102, v90, v91
	v_max3_f32 v102, v102, v92, v93
	v_max3_f32 v102, v102, v94, v95
	v_max3_f32 v102, v102, v96, v97
	v_max3_f32 v102, v102, v98, v99
	v_max3_f32 v102, v102, v100, v101
	v_max3_f32 v102, v102, v114, v115
	v_max3_f32 v102, v102, v116, v117
	v_max3_f32 v102, v102, v118, v119
	v_max3_f32 v102, v102, v120, v121
	v_max3_f32 v102, v102, v122, v123
	v_max3_f32 v102, v102, v124, v125
	v_max3_f32 v102, v102, v126, v127
	v_max3_f32 v102, v102, v128, v129
	v_mov_b32_e32 v103, v102
	s_nop 1
	v_permlane32_swap_b32_e32 v102, v103
	v_max_f32_e32 v102, v102, v103
	v_sub_f32_e32 v103, v102, v233
	v_cmp_ge_f32_e32 vcc, s46, v103
	s_cmp_eq_u64 vcc, exec
	v_max_f32_e32 v103, v233, v233
	v_max_f32_e32 v193, v103, v102
	s_cselect_b64 vcc, -1, 0
	v_cndmask_b32_e32 v235, v193, v233, vcc
	v_fma_f32 v192, v235, s47, 4.0
	v_mfma_f32_32x32x64_f8f6f4 v[18:33], v[130:137], v[236:243], v[18:33]
	v_pk_add_f32 v[82:83], v[82:83], v[84:85]
	v_pk_fma_f32 v[110:111], v[98:99], s[6:7], v[192:193] op_sel_hi:[1,0,0]
	v_pk_fma_f32 v[98:99], v[86:87], s[6:7], v[192:193] op_sel_hi:[1,0,0]
	ds_read_b64_tr_b8 v[86:87], v206 offset:0
	v_pk_fma_f32 v[112:113], v[100:101], s[6:7], v[192:193] op_sel_hi:[1,0,0]
	v_pk_fma_f32 v[100:101], v[88:89], s[6:7], v[192:193] op_sel_hi:[1,0,0]
	ds_read_b64_tr_b8 v[88:89], v206 offset:0x800
	v_pk_fma_f32 v[102:103], v[90:91], s[6:7], v[192:193] op_sel_hi:[1,0,0]
	ds_read_b64_tr_b8 v[90:91], v206 offset:0x1000
	v_pk_fma_f32 v[108:109], v[96:97], s[6:7], v[192:193] op_sel_hi:[1,0,0]
	v_pk_fma_f32 v[106:107], v[94:95], s[6:7], v[192:193] op_sel_hi:[1,0,0]
	v_pk_fma_f32 v[104:105], v[92:93], s[6:7], v[192:193] op_sel_hi:[1,0,0]
	v_pk_fma_f32 v[128:129], v[128:129], s[6:7], v[192:193] op_sel_hi:[1,0,0]
	v_pk_fma_f32 v[126:127], v[126:127], s[6:7], v[192:193] op_sel_hi:[1,0,0]
	v_pk_fma_f32 v[124:125], v[124:125], s[6:7], v[192:193] op_sel_hi:[1,0,0]
	v_pk_fma_f32 v[122:123], v[122:123], s[6:7], v[192:193] op_sel_hi:[1,0,0]
	v_pk_fma_f32 v[120:121], v[120:121], s[6:7], v[192:193] op_sel_hi:[1,0,0]
	v_pk_fma_f32 v[118:119], v[118:119], s[6:7], v[192:193] op_sel_hi:[1,0,0]
	v_pk_fma_f32 v[116:117], v[116:117], s[6:7], v[192:193] op_sel_hi:[1,0,0]
	v_pk_fma_f32 v[114:115], v[114:115], s[6:7], v[192:193] op_sel_hi:[1,0,0]
	ds_read_b64_tr_b8 v[92:93], v206 offset:0x1800
	s_waitcnt lgkmcnt(4)
	v_pk_add_f32 v[82:83], v[190:191], v[82:83]
	v_mfma_f32_32x32x64_f8f6f4 v[34:49], v[130:137], v[244:251], v[34:49]
	s_waitcnt lgkmcnt(0)
	s_nop 0
	v_exp_f32_e32 v98, v98
	v_exp_f32_e32 v99, v99
	v_exp_f32_e32 v100, v100
	v_exp_f32_e32 v101, v101
	v_mfma_f32_32x32x64_f8f6f4 v[50:65], v[130:137], v[86:93], v[50:65]
	s_barrier
	global_load_lds_dwordx4 v[184:185], off
	v_pk_add_f32 v[82:83], v[188:189], v[82:83]
	s_nop 0
	v_pk_add_f32 v[82:83], v[144:145], v[82:83]
	s_nop 0
	v_pk_add_f32 v[82:83], v[138:139], v[82:83]
	s_nop 0
	v_pk_add_f32 v[82:83], v[142:143], v[82:83]
	s_nop 0
	v_pk_add_f32 v[82:83], v[140:141], v[82:83]
	s_nop 0
	v_pk_add_f32 v[66:67], v[82:83], v[66:67]
	s_nop 0
	v_pk_add_f32 v[66:67], v[68:69], v[66:67]
	s_nop 0
	v_pk_add_f32 v[66:67], v[70:71], v[66:67]
	s_nop 0
	v_pk_add_f32 v[66:67], v[72:73], v[66:67]
	s_nop 0
	v_pk_add_f32 v[66:67], v[74:75], v[66:67]
	s_nop 0
	v_pk_add_f32 v[66:67], v[76:77], v[66:67]
	s_nop 0
	v_pk_add_f32 v[66:67], v[78:79], v[66:67]
	s_nop 0
	v_pk_add_f32 v[66:67], v[80:81], v[66:67]
	s_nop 0
	v_pk_add_f32 v[188:189], v[66:67], v[66:67] op_sel:[0,1] op_sel_hi:[1,0]
	v_sub_f32_e32 v66, v233, v193
	v_mul_f32_e32 v66, 0x3dd53b94, v66
	v_exp_f32_e32 v66, v66
	v_mov_b32_e32 v234, v188
	s_nop 1
	v_permlane32_swap_b32_e32 v188, v234
	v_cndmask_b32_e64 v189, v66, 1.0, vcc
	v_cmp_gt_f32_e32 vcc, 1.0, v189
	s_cbranch_vccz .LBB0_511
	s_and_saveexec_b64 s[24:25], s[2:3]
	ds_write_b32 v207, v189 offset:128
	s_or_b64 exec, exec, s[24:25]
	s_waitcnt lgkmcnt(0)
	s_nop 15
	s_nop 7
	ds_read2_b32 v[66:67], v205 offset0:32 offset1:33
	ds_read2_b32 v[68:69], v205 offset0:34 offset1:35
	ds_read2_b32 v[70:71], v205 offset0:40 offset1:41
	ds_read2_b32 v[72:73], v205 offset0:42 offset1:43
	s_waitcnt lgkmcnt(0)
	v_pk_mul_f32 v[2:3], v[66:67], v[2:3]
	v_pk_mul_f32 v[18:19], v[66:67], v[18:19]
	v_pk_mul_f32 v[34:35], v[66:67], v[34:35]
	v_pk_mul_f32 v[50:51], v[66:67], v[50:51]
	v_pk_mul_f32 v[4:5], v[4:5], v[68:69]
	v_pk_mul_f32 v[20:21], v[20:21], v[68:69]
	v_pk_mul_f32 v[36:37], v[36:37], v[68:69]
	v_pk_mul_f32 v[52:53], v[52:53], v[68:69]
	v_pk_mul_f32 v[6:7], v[6:7], v[70:71]
	v_pk_mul_f32 v[22:23], v[22:23], v[70:71]
	v_pk_mul_f32 v[38:39], v[38:39], v[70:71]
	v_pk_mul_f32 v[54:55], v[54:55], v[70:71]
	v_pk_mul_f32 v[8:9], v[8:9], v[72:73]
	v_pk_mul_f32 v[24:25], v[24:25], v[72:73]
	v_pk_mul_f32 v[40:41], v[40:41], v[72:73]
	ds_read2_b32 v[66:67], v205 offset0:48 offset1:49
	v_pk_mul_f32 v[56:57], v[56:57], v[72:73]
	ds_read2_b32 v[68:69], v205 offset0:50 offset1:51
	ds_read2_b32 v[70:71], v205 offset0:56 offset1:57
	ds_read2_b32 v[72:73], v205 offset0:58 offset1:59
	s_waitcnt lgkmcnt(0)
	v_pk_mul_f32 v[10:11], v[10:11], v[66:67]
	v_pk_mul_f32 v[26:27], v[26:27], v[66:67]
	v_pk_mul_f32 v[42:43], v[42:43], v[66:67]
	v_pk_mul_f32 v[58:59], v[58:59], v[66:67]
	v_pk_mul_f32 v[12:13], v[12:13], v[68:69]
	v_pk_mul_f32 v[28:29], v[28:29], v[68:69]
	v_pk_mul_f32 v[44:45], v[44:45], v[68:69]
	v_pk_mul_f32 v[60:61], v[60:61], v[68:69]
	v_pk_mul_f32 v[14:15], v[14:15], v[70:71]
	v_pk_mul_f32 v[30:31], v[30:31], v[70:71]
	v_pk_mul_f32 v[46:47], v[46:47], v[70:71]
	v_pk_mul_f32 v[62:63], v[62:63], v[70:71]
	v_pk_mul_f32 v[16:17], v[16:17], v[72:73]
	v_pk_mul_f32 v[32:33], v[32:33], v[72:73]
	v_pk_mul_f32 v[48:49], v[48:49], v[72:73]
	v_pk_mul_f32 v[64:65], v[64:65], v[72:73]
.LBB0_511:
	s_add_i32 s24, s23, 1
	s_cmp_lt_u32 s24, s56
	s_cselect_b32 s24, 0, s56
	s_cselect_b32 s25, s22, 0
	s_lshl_b32 s24, s24, 6
	s_ashr_i32 s29, s25, 31
	s_sub_i32 s24, s28, s24
	s_add_u32 s60, s24, s25
	s_addc_u32 s61, 0, s29
	s_waitcnt vmcnt(1)
	s_lshl_b64 s[24:25], s[60:61], 11
	s_add_i32 s59, s55, 0xc000
	s_barrier
	v_lshl_add_u64 v[66:67], v[176:177], 0, s[24:25]
	s_mov_b32 m0, s59
	s_lshl_b64 s[60:61], s[60:61], 6
	s_add_i32 s29, s38, s57
	global_load_lds_dwordx4 v[66:67], off
	v_lshl_add_u64 v[66:67], v[178:179], 0, s[60:61]
	s_mov_b32 m0, s29
	v_exp_f32_e32 v190, v102
	global_load_lds_dwordx4 v[66:67], off
	v_exp_f32_e32 v191, v103
	v_exp_f32_e32 v192, v104
	v_exp_f32_e32 v193, v105
	v_exp_f32_e32 v194, v106
	v_exp_f32_e32 v195, v107
	v_exp_f32_e32 v196, v108
	v_exp_f32_e32 v197, v109
	v_exp_f32_e32 v110, v110
	v_exp_f32_e32 v111, v111
	v_exp_f32_e32 v112, v112
	v_exp_f32_e32 v113, v113
	ds_read_b128 v[82:85], v213 offset:32768
	ds_read_b128 v[86:89], v214 offset:32768
	ds_read_b128 v[90:93], v215 offset:32768
	ds_read_b128 v[94:97], v216 offset:32768
	v_mov_b32_e32 v102, 0
	v_mov_b32_e32 v103, 0
	s_waitcnt lgkmcnt(0)
	v_mfma_f32_32x32x64_f8f6f4 v[66:81], v[82:89], v[146:153], 0
	ds_read_b128 v[82:85], v217 offset:32768
	ds_read_b128 v[86:89], v218 offset:32768
	v_exp_f32_e32 v114, v114
	v_exp_f32_e32 v115, v115
	v_exp_f32_e32 v116, v116
	v_mfma_f32_32x32x64_f8f6f4 v[130:145], v[90:97], v[146:153], 0
	ds_read_b128 v[90:93], v211 offset:32768
	ds_read_b128 v[94:97], v212 offset:32768
	v_exp_f32_e32 v117, v117
	v_exp_f32_e32 v118, v118
	v_exp_f32_e32 v119, v119
	s_waitcnt lgkmcnt(0)
	v_mfma_f32_32x32x64_f8f6f4 v[66:81], v[82:89], v[154:161], v[66:81]
	ds_read_b128 v[82:85], v220
	ds_read_b128 v[86:89], v222
	v_exp_f32_e32 v120, v120
	v_exp_f32_e32 v121, v121
	v_exp_f32_e32 v122, v122
	v_mfma_f32_32x32x64_f8f6f4 v[130:145], v[90:97], v[154:161], v[130:145]
	ds_read_b128 v[90:93], v223
	ds_read_b128 v[94:97], v224
	v_exp_f32_e32 v123, v123
	v_exp_f32_e32 v124, v124
	v_exp_f32_e32 v125, v125
	s_waitcnt lgkmcnt(0)
	v_mfma_f32_32x32x64_f8f6f4 v[66:81], v[82:89], v[162:169], v[66:81]
	v_exp_f32_e32 v126, v126
	v_exp_f32_e32 v127, v127
	v_mfma_f32_32x32x64_f8f6f4 v[130:145], v[90:97], v[162:169], v[130:145]
	ds_read_b64_tr_b8 v[82:83], v204 offset:0
	ds_read_b64_tr_b8 v[84:85], v204 offset:0x800
	ds_read_b64_tr_b8 v[86:87], v204 offset:0x1000
	ds_read_b64_tr_b8 v[88:89], v204 offset:0x1800
	v_cvt_pk_fp8_f32 v102, v98, v99
	v_cvt_pk_fp8_f32 v103, v190, v191
	v_cvt_pk_fp8_f32 v104, v194, v195
	v_cvt_pk_fp8_f32 v105, v110, v111
	v_exp_f32_e32 v128, v128
	v_cvt_pk_fp8_f32 v106, v114, v115
	v_cvt_pk_fp8_f32 v107, v118, v119
	v_exp_f32_e32 v129, v129
	v_cvt_pk_fp8_f32 v108, v122, v123
	v_cvt_pk_fp8_f32 v109, v126, v127
	ds_read_b64_tr_b8 v[90:91], v203 offset:0
	ds_read_b64_tr_b8 v[92:93], v203 offset:0x800
	ds_read_b64_tr_b8 v[94:95], v203 offset:0x1000
	ds_read_b64_tr_b8 v[96:97], v203 offset:0x1800
	v_cvt_pk_fp8_f32 v102, v100, v101 op_sel:[0,0,1]
	v_cvt_pk_fp8_f32 v103, v192, v193 op_sel:[0,0,1]
	v_cvt_pk_fp8_f32 v106, v116, v117 op_sel:[0,0,1]
	v_cvt_pk_fp8_f32 v107, v120, v121 op_sel:[0,0,1]
	v_cvt_pk_fp8_f32 v104, v196, v197 op_sel:[0,0,1]
	v_cvt_pk_fp8_f32 v108, v124, v125 op_sel:[0,0,1]
	v_cvt_pk_fp8_f32 v105, v112, v113 op_sel:[0,0,1]
	v_cvt_pk_fp8_f32 v109, v128, v129 op_sel:[0,0,1]
	s_waitcnt lgkmcnt(4)
	s_mov_b32 m0, s58
	v_mfma_f32_32x32x64_f8f6f4 v[2:17], v[102:109], v[82:89], v[2:17]
	ds_read_b64_tr_b8 v[236:237], v202 offset:0
	ds_read_b64_tr_b8 v[238:239], v202 offset:0x800
	ds_read_b64_tr_b8 v[240:241], v202 offset:0x1000
	ds_read_b64_tr_b8 v[242:243], v202 offset:0x1800
	s_waitcnt lgkmcnt(4)
	s_nop 0
	v_max_f32_e32 v82, v66, v67
	v_max3_f32 v82, v82, v68, v69
	v_max3_f32 v82, v82, v70, v71
	v_max3_f32 v82, v82, v72, v73
	v_max3_f32 v82, v82, v74, v75
	v_max3_f32 v82, v82, v76, v77
	v_max3_f32 v82, v82, v78, v79
	v_max3_f32 v82, v82, v80, v81
	v_max3_f32 v82, v82, v130, v131
	v_max3_f32 v82, v82, v132, v133
	v_max3_f32 v82, v82, v134, v135
	v_max3_f32 v82, v82, v136, v137
	v_max3_f32 v82, v82, v138, v139
	v_max3_f32 v82, v82, v140, v141
	v_max3_f32 v82, v82, v142, v143
	v_max3_f32 v82, v82, v144, v145
	v_mov_b32_e32 v83, v82
	s_nop 1
	v_permlane32_swap_b32_e32 v82, v83
	v_max_f32_e32 v82, v82, v83
	v_sub_f32_e32 v83, v82, v235
	v_cmp_ge_f32_e32 vcc, s46, v83
	s_cmp_eq_u64 vcc, exec
	v_max_f32_e32 v83, v235, v235
	v_max_f32_e32 v245, v83, v82
	s_cselect_b64 vcc, -1, 0
	v_cndmask_b32_e32 v233, v245, v235, vcc
	v_fma_f32 v244, v233, s47, 4.0
	v_mfma_f32_32x32x64_f8f6f4 v[18:33], v[102:109], v[90:97], v[18:33]
	v_pk_add_f32 v[98:99], v[98:99], v[100:101]
	v_pk_fma_f32 v[82:83], v[66:67], s[6:7], v[244:245] op_sel_hi:[1,0,0]
	v_pk_fma_f32 v[66:67], v[130:131], s[6:7], v[244:245] op_sel_hi:[1,0,0]
	ds_read_b64_tr_b8 v[130:131], v201 offset:0
	v_pk_fma_f32 v[84:85], v[68:69], s[6:7], v[244:245] op_sel_hi:[1,0,0]
	v_pk_fma_f32 v[68:69], v[132:133], s[6:7], v[244:245] op_sel_hi:[1,0,0]
	ds_read_b64_tr_b8 v[132:133], v201 offset:0x800
	v_pk_fma_f32 v[86:87], v[70:71], s[6:7], v[244:245] op_sel_hi:[1,0,0]
	v_pk_fma_f32 v[70:71], v[134:135], s[6:7], v[244:245] op_sel_hi:[1,0,0]
	ds_read_b64_tr_b8 v[134:135], v201 offset:0x1000
	v_pk_fma_f32 v[96:97], v[80:81], s[6:7], v[244:245] op_sel_hi:[1,0,0]
	v_pk_fma_f32 v[94:95], v[78:79], s[6:7], v[244:245] op_sel_hi:[1,0,0]
	v_pk_fma_f32 v[92:93], v[76:77], s[6:7], v[244:245] op_sel_hi:[1,0,0]
	v_pk_fma_f32 v[90:91], v[74:75], s[6:7], v[244:245] op_sel_hi:[1,0,0]
	v_pk_fma_f32 v[88:89], v[72:73], s[6:7], v[244:245] op_sel_hi:[1,0,0]
	v_pk_fma_f32 v[80:81], v[144:145], s[6:7], v[244:245] op_sel_hi:[1,0,0]
	v_pk_fma_f32 v[78:79], v[142:143], s[6:7], v[244:245] op_sel_hi:[1,0,0]
	v_pk_fma_f32 v[76:77], v[140:141], s[6:7], v[244:245] op_sel_hi:[1,0,0]
	v_pk_fma_f32 v[74:75], v[138:139], s[6:7], v[244:245] op_sel_hi:[1,0,0]
	v_pk_fma_f32 v[72:73], v[136:137], s[6:7], v[244:245] op_sel_hi:[1,0,0]
	ds_read_b64_tr_b8 v[136:137], v201 offset:0x1800
	s_waitcnt lgkmcnt(4)
	v_pk_add_f32 v[98:99], v[98:99], v[190:191]
	v_mfma_f32_32x32x64_f8f6f4 v[34:49], v[102:109], v[236:243], v[34:49]
	s_waitcnt lgkmcnt(0)
	s_nop 0
	v_exp_f32_e32 v82, v82
	v_exp_f32_e32 v83, v83
	v_exp_f32_e32 v84, v84
	v_exp_f32_e32 v85, v85
	v_mfma_f32_32x32x64_f8f6f4 v[50:65], v[102:109], v[130:137], v[50:65]
	s_barrier
	v_lshl_add_u64 v[102:103], v[180:181], 0, s[24:25]
	global_load_lds_dwordx4 v[102:103], off
	v_pk_add_f32 v[98:99], v[192:193], v[98:99]
	s_nop 0
	v_pk_add_f32 v[98:99], v[194:195], v[98:99]
	s_nop 0
	v_pk_add_f32 v[98:99], v[196:197], v[98:99]
	s_nop 0
	v_pk_add_f32 v[98:99], v[110:111], v[98:99]
	s_nop 0
	v_pk_add_f32 v[98:99], v[112:113], v[98:99]
	s_nop 0
	v_pk_add_f32 v[98:99], v[98:99], v[114:115]
	s_nop 0
	v_pk_add_f32 v[98:99], v[116:117], v[98:99]
	s_nop 0
	v_pk_add_f32 v[98:99], v[118:119], v[98:99]
	s_nop 0
	v_pk_add_f32 v[98:99], v[120:121], v[98:99]
	s_nop 0
	v_pk_add_f32 v[98:99], v[122:123], v[98:99]
	s_nop 0
	v_pk_add_f32 v[98:99], v[124:125], v[98:99]
	s_nop 0
	v_pk_add_f32 v[98:99], v[126:127], v[98:99]
	s_nop 0
	v_pk_add_f32 v[98:99], v[128:129], v[98:99]
	s_nop 0
	v_pk_add_f32 v[98:99], v[98:99], v[98:99] op_sel:[0,1] op_sel_hi:[1,0]
	s_nop 0
	v_sub_f32_e32 v99, v235, v245
	v_mul_f32_e32 v99, 0x3dd53b94, v99
	v_exp_f32_e32 v100, v99
	v_mov_b32_e32 v99, v98
	s_nop 1
	v_permlane32_swap_b32_e32 v98, v99
	v_cndmask_b32_e64 v128, v100, 1.0, vcc
	v_cmp_gt_f32_e32 vcc, 1.0, v128
	s_cbranch_vccz .LBB0_515
	s_and_saveexec_b64 s[24:25], s[2:3]
	ds_write_b32 v207, v128 offset:128
	s_or_b64 exec, exec, s[24:25]
	s_waitcnt lgkmcnt(0)
	s_nop 15
	s_nop 7
	ds_read2_b32 v[100:101], v205 offset0:32 offset1:33
	ds_read2_b32 v[102:103], v205 offset0:34 offset1:35
	ds_read2_b32 v[104:105], v205 offset0:40 offset1:41
	ds_read2_b32 v[106:107], v205 offset0:42 offset1:43
	s_waitcnt lgkmcnt(0)
	v_pk_mul_f32 v[2:3], v[100:101], v[2:3]
	v_pk_mul_f32 v[18:19], v[100:101], v[18:19]
	v_pk_mul_f32 v[34:35], v[100:101], v[34:35]
	v_pk_mul_f32 v[50:51], v[100:101], v[50:51]
	v_pk_mul_f32 v[4:5], v[4:5], v[102:103]
	v_pk_mul_f32 v[20:21], v[20:21], v[102:103]
	v_pk_mul_f32 v[36:37], v[36:37], v[102:103]
	v_pk_mul_f32 v[52:53], v[52:53], v[102:103]
	v_pk_mul_f32 v[6:7], v[6:7], v[104:105]
	v_pk_mul_f32 v[22:23], v[22:23], v[104:105]
	v_pk_mul_f32 v[38:39], v[38:39], v[104:105]
	v_pk_mul_f32 v[54:55], v[54:55], v[104:105]
	v_pk_mul_f32 v[8:9], v[8:9], v[106:107]
	v_pk_mul_f32 v[24:25], v[24:25], v[106:107]
	v_pk_mul_f32 v[40:41], v[40:41], v[106:107]
	ds_read2_b32 v[100:101], v205 offset0:48 offset1:49
	v_pk_mul_f32 v[56:57], v[56:57], v[106:107]
	ds_read2_b32 v[102:103], v205 offset0:50 offset1:51
	ds_read2_b32 v[104:105], v205 offset0:56 offset1:57
	ds_read2_b32 v[106:107], v205 offset0:58 offset1:59
	s_waitcnt lgkmcnt(0)
	v_pk_mul_f32 v[10:11], v[10:11], v[100:101]
	v_pk_mul_f32 v[26:27], v[26:27], v[100:101]
	v_pk_mul_f32 v[42:43], v[42:43], v[100:101]
	v_pk_mul_f32 v[58:59], v[58:59], v[100:101]
	v_pk_mul_f32 v[12:13], v[12:13], v[102:103]
	v_pk_mul_f32 v[28:29], v[28:29], v[102:103]
	v_pk_mul_f32 v[44:45], v[44:45], v[102:103]
	v_pk_mul_f32 v[60:61], v[60:61], v[102:103]
	v_pk_mul_f32 v[14:15], v[14:15], v[104:105]
	v_pk_mul_f32 v[30:31], v[30:31], v[104:105]
	v_pk_mul_f32 v[46:47], v[46:47], v[104:105]
	v_pk_mul_f32 v[62:63], v[62:63], v[104:105]
	v_pk_mul_f32 v[16:17], v[16:17], v[106:107]
	v_pk_mul_f32 v[32:33], v[32:33], v[106:107]
	v_pk_mul_f32 v[48:49], v[48:49], v[106:107]
	v_pk_mul_f32 v[64:65], v[64:65], v[106:107]

.LBB0_517:
	ds_read_b128 v[102:105], v213 offset:49152
	ds_read_b128 v[106:109], v214 offset:49152
	ds_read_b128 v[120:123], v215 offset:49152
	ds_read_b128 v[124:127], v216 offset:49152
	v_mov_b32_e32 v118, v171
	v_cvt_pk_fp8_f32 v118, v82, v83
	s_waitcnt lgkmcnt(0)
	v_mfma_f32_32x32x64_f8f6f4 v[86:101], v[102:109], v[146:153], 0
	ds_read_b128 v[130:133], v217 offset:49152
	ds_read_b128 v[134:137], v218 offset:49152
	v_exp_f32_e32 v66, v66
	v_exp_f32_e32 v67, v67
	v_exp_f32_e32 v68, v68
	v_pk_add_f32 v[102:103], v[82:83], v[84:85]
	v_mov_b32_e32 v119, v171
	v_pk_add_f32 v[176:177], v[102:103], v[190:191]
	v_mfma_f32_32x32x64_f8f6f4 v[102:117], v[120:127], v[146:153], 0
	ds_read_b128 v[120:123], v211 offset:49152
	ds_read_b128 v[124:127], v212 offset:49152
	v_exp_f32_e32 v69, v69
	v_exp_f32_e32 v70, v70
	v_exp_f32_e32 v71, v71
	s_waitcnt lgkmcnt(0)
	v_mfma_f32_32x32x64_f8f6f4 v[86:101], v[130:137], v[154:161], v[86:101]
	ds_read_b128 v[130:133], v228
	ds_read_b128 v[134:137], v229
	v_exp_f32_e32 v72, v72
	v_exp_f32_e32 v73, v73
	v_exp_f32_e32 v74, v74
	v_mfma_f32_32x32x64_f8f6f4 v[102:117], v[120:127], v[154:161], v[102:117]
	v_pk_add_f32 v[82:83], v[176:177], v[188:189]
	ds_read_b128 v[146:149], v231
	ds_read_b128 v[150:153], v232
	v_pk_add_f32 v[82:83], v[82:83], v[144:145]
	v_exp_f32_e32 v75, v75
	v_exp_f32_e32 v76, v76
	v_exp_f32_e32 v77, v77
	v_pk_add_f32 v[82:83], v[82:83], v[138:139]
	s_waitcnt lgkmcnt(0)
	v_mfma_f32_32x32x64_f8f6f4 v[86:101], v[130:137], v[162:169], v[86:101]
	v_mov_b32_e32 v122, v171
	v_pk_add_f32 v[82:83], v[82:83], v[142:143]
	v_exp_f32_e32 v78, v78
	v_exp_f32_e32 v79, v79
	v_pk_add_f32 v[82:83], v[82:83], v[140:141]
	v_mfma_f32_32x32x64_f8f6f4 v[102:117], v[146:153], v[162:169], v[102:117]
	v_mov_b32_e32 v123, v171
	v_pk_add_f32 v[82:83], v[82:83], v[66:67]
	v_cvt_pk_fp8_f32 v122, v66, v67
	v_pk_add_f32 v[66:67], v[68:69], v[82:83]
	v_exp_f32_e32 v80, v80
	v_pk_add_f32 v[66:67], v[70:71], v[66:67]
	v_exp_f32_e32 v81, v81
	v_pk_add_f32 v[66:67], v[72:73], v[66:67]
	v_cvt_pk_fp8_f32 v123, v70, v71
	v_pk_add_f32 v[66:67], v[74:75], v[66:67]
	v_mov_b32_e32 v124, v171
	v_pk_add_f32 v[66:67], v[76:77], v[66:67]
	v_cvt_pk_fp8_f32 v122, v68, v69 op_sel:[0,0,1]
	v_pk_add_f32 v[66:67], v[78:79], v[66:67]
	v_cvt_pk_fp8_f32 v124, v74, v75
	v_pk_add_f32 v[66:67], v[80:81], v[66:67]
	v_mov_b32_e32 v125, v171
	v_pk_add_f32 v[126:127], v[66:67], v[66:67] op_sel:[0,1] op_sel_hi:[1,0]
	ds_read_b64_tr_b8 v[66:67], v208 offset:0
	ds_read_b64_tr_b8 v[68:69], v208 offset:0x800
	ds_read_b64_tr_b8 v[70:71], v208 offset:0x1000
	v_cvt_pk_fp8_f32 v123, v72, v73 op_sel:[0,0,1]
	v_mov_b32_e32 v120, v171
	v_mov_b32_e32 v121, v171
	v_cvt_pk_fp8_f32 v125, v78, v79
	ds_read_b64_tr_b8 v[72:73], v208 offset:0x1800
	v_cvt_pk_fp8_f32 v119, v190, v191
	v_cvt_pk_fp8_f32 v120, v144, v145
	v_cvt_pk_fp8_f32 v121, v142, v143
	ds_read_b64_tr_b8 v[74:75], v210 offset:0
	v_cvt_pk_fp8_f32 v124, v76, v77 op_sel:[0,0,1]
	ds_read_b64_tr_b8 v[76:77], v210 offset:0x800
	ds_read_b64_tr_b8 v[78:79], v210 offset:0x1000
	v_cvt_pk_fp8_f32 v125, v80, v81 op_sel:[0,0,1]
	ds_read_b64_tr_b8 v[80:81], v210 offset:0x1800
	v_cvt_pk_fp8_f32 v118, v84, v85 op_sel:[0,0,1]
	v_cvt_pk_fp8_f32 v119, v188, v189 op_sel:[0,0,1]
	v_cvt_pk_fp8_f32 v120, v138, v139 op_sel:[0,0,1]
	v_cvt_pk_fp8_f32 v121, v140, v141 op_sel:[0,0,1]
	s_waitcnt lgkmcnt(4)
	v_mov_b32_e32 v127, v126
	v_mfma_f32_32x32x64_f8f6f4 v[2:17], v[118:125], v[66:73], v[2:17]
	ds_read_b64_tr_b8 v[130:131], v209 offset:0
	ds_read_b64_tr_b8 v[132:133], v209 offset:0x800
	ds_read_b64_tr_b8 v[134:135], v209 offset:0x1000
	ds_read_b64_tr_b8 v[136:137], v209 offset:0x1800
	s_waitcnt lgkmcnt(4)
	s_nop 0
	v_max_f32_e32 v66, v86, v87
	v_max3_f32 v66, v66, v88, v89
	v_max3_f32 v66, v66, v90, v91
	v_max3_f32 v66, v66, v92, v93
	v_max3_f32 v66, v66, v94, v95
	v_max3_f32 v66, v66, v96, v97
	v_max3_f32 v66, v66, v98, v99
	v_max3_f32 v66, v66, v100, v101
	v_max3_f32 v66, v66, v102, v103
	v_max3_f32 v66, v66, v104, v105
	v_max3_f32 v66, v66, v106, v107
	v_max3_f32 v66, v66, v108, v109
	v_max3_f32 v66, v66, v110, v111
	v_max3_f32 v66, v66, v112, v113
	v_max3_f32 v66, v66, v114, v115
	v_max3_f32 v66, v66, v116, v117
	v_mov_b32_e32 v67, v66
	s_nop 1
	v_permlane32_swap_b32_e32 v66, v67
	v_max_f32_e32 v66, v66, v67
	v_sub_f32_e32 v67, v66, v233
	v_cmp_ge_f32_e32 vcc, s46, v67
	s_cmp_eq_u64 vcc, exec
	v_max_f32_e32 v66, v233, v66
	s_cselect_b64 vcc, -1, 0
	v_sub_f32_e32 v67, v233, v66
	v_cndmask_b32_e32 v66, v66, v233, vcc
	v_mul_f32_e32 v83, 0x3dd53b94, v67
	v_fma_f32 v82, v66, s47, 4.0
	v_mfma_f32_32x32x64_f8f6f4 v[18:33], v[118:125], v[74:81], v[18:33]
	v_permlane32_swap_b32_e32 v126, v127
	v_pk_fma_f32 v[80:81], v[100:101], s[6:7], v[82:83] op_sel_hi:[1,0,0]
	ds_read_b64_tr_b8 v[100:101], v206 offset:0
	v_pk_fma_f32 v[78:79], v[98:99], s[6:7], v[82:83] op_sel_hi:[1,0,0]
	v_pk_fma_f32 v[76:77], v[96:97], s[6:7], v[82:83] op_sel_hi:[1,0,0]
	v_pk_fma_f32 v[74:75], v[94:95], s[6:7], v[82:83] op_sel_hi:[1,0,0]
	v_pk_fma_f32 v[72:73], v[92:93], s[6:7], v[82:83] op_sel_hi:[1,0,0]
	v_pk_fma_f32 v[70:71], v[90:91], s[6:7], v[82:83] op_sel_hi:[1,0,0]
	v_pk_fma_f32 v[68:69], v[88:89], s[6:7], v[82:83] op_sel_hi:[1,0,0]
	v_pk_fma_f32 v[66:67], v[86:87], s[6:7], v[82:83] op_sel_hi:[1,0,0]
	v_exp_f32_e32 v98, v83
	v_pk_fma_f32 v[96:97], v[116:117], s[6:7], v[82:83] op_sel_hi:[1,0,0]
	v_pk_fma_f32 v[94:95], v[114:115], s[6:7], v[82:83] op_sel_hi:[1,0,0]
	v_pk_fma_f32 v[92:93], v[112:113], s[6:7], v[82:83] op_sel_hi:[1,0,0]
	v_pk_fma_f32 v[90:91], v[110:111], s[6:7], v[82:83] op_sel_hi:[1,0,0]
	v_pk_fma_f32 v[88:89], v[108:109], s[6:7], v[82:83] op_sel_hi:[1,0,0]
	v_pk_fma_f32 v[86:87], v[106:107], s[6:7], v[82:83] op_sel_hi:[1,0,0]
	v_pk_fma_f32 v[84:85], v[104:105], s[6:7], v[82:83] op_sel_hi:[1,0,0]
	v_pk_fma_f32 v[82:83], v[102:103], s[6:7], v[82:83] op_sel_hi:[1,0,0]
	ds_read_b64_tr_b8 v[102:103], v206 offset:0x800
	ds_read_b64_tr_b8 v[104:105], v206 offset:0x1000
	ds_read_b64_tr_b8 v[106:107], v206 offset:0x1800
	s_waitcnt lgkmcnt(4)
	v_cndmask_b32_e64 v98, v98, 1.0, vcc
	v_mfma_f32_32x32x64_f8f6f4 v[34:49], v[118:125], v[130:137], v[34:49]
	s_waitcnt lgkmcnt(0)
	v_cmp_gt_f32_e32 vcc, 1.0, v98
	v_exp_f32_e32 v66, v66
	v_exp_f32_e32 v67, v67
	v_exp_f32_e32 v68, v68
	v_exp_f32_e32 v69, v69
	v_mfma_f32_32x32x64_f8f6f4 v[50:65], v[118:125], v[100:107], v[50:65]
	s_cbranch_vccz .LBB0_521
	s_and_saveexec_b64 s[22:23], s[2:3]
	ds_write_b32 v207, v98 offset:128
	s_or_b64 exec, exec, s[22:23]
	s_waitcnt lgkmcnt(0)
	s_nop 15
	s_nop 7
	ds_read2_b32 v[100:101], v205 offset0:32 offset1:33
	ds_read2_b32 v[102:103], v205 offset0:34 offset1:35
	ds_read2_b32 v[104:105], v205 offset0:40 offset1:41
	ds_read2_b32 v[106:107], v205 offset0:42 offset1:43
	s_waitcnt lgkmcnt(0)
	v_pk_mul_f32 v[2:3], v[100:101], v[2:3]
	v_pk_mul_f32 v[18:19], v[100:101], v[18:19]
	v_pk_mul_f32 v[34:35], v[100:101], v[34:35]
	v_pk_mul_f32 v[50:51], v[100:101], v[50:51]
	v_pk_mul_f32 v[4:5], v[4:5], v[102:103]
	v_pk_mul_f32 v[20:21], v[20:21], v[102:103]
	v_pk_mul_f32 v[36:37], v[36:37], v[102:103]
	v_pk_mul_f32 v[52:53], v[52:53], v[102:103]
	v_pk_mul_f32 v[6:7], v[6:7], v[104:105]
	v_pk_mul_f32 v[22:23], v[22:23], v[104:105]
	v_pk_mul_f32 v[38:39], v[38:39], v[104:105]
	v_pk_mul_f32 v[54:55], v[54:55], v[104:105]
	v_pk_mul_f32 v[8:9], v[8:9], v[106:107]
	v_pk_mul_f32 v[24:25], v[24:25], v[106:107]
	v_pk_mul_f32 v[40:41], v[40:41], v[106:107]
	ds_read2_b32 v[100:101], v205 offset0:48 offset1:49
	v_pk_mul_f32 v[56:57], v[56:57], v[106:107]
	ds_read2_b32 v[102:103], v205 offset0:50 offset1:51
	ds_read2_b32 v[104:105], v205 offset0:56 offset1:57
	ds_read2_b32 v[106:107], v205 offset0:58 offset1:59
	s_waitcnt lgkmcnt(0)
	v_pk_mul_f32 v[10:11], v[10:11], v[100:101]
	v_pk_mul_f32 v[26:27], v[26:27], v[100:101]
	v_pk_mul_f32 v[42:43], v[42:43], v[100:101]
	v_pk_mul_f32 v[58:59], v[58:59], v[100:101]
	v_pk_mul_f32 v[12:13], v[12:13], v[102:103]
	v_pk_mul_f32 v[28:29], v[28:29], v[102:103]
	v_pk_mul_f32 v[44:45], v[44:45], v[102:103]
	v_pk_mul_f32 v[60:61], v[60:61], v[102:103]
	v_pk_mul_f32 v[14:15], v[14:15], v[104:105]
	v_pk_mul_f32 v[30:31], v[30:31], v[104:105]
	v_pk_mul_f32 v[46:47], v[46:47], v[104:105]
	v_pk_mul_f32 v[62:63], v[62:63], v[104:105]
	v_pk_mul_f32 v[16:17], v[16:17], v[106:107]
	v_pk_mul_f32 v[32:33], v[32:33], v[106:107]
	v_pk_mul_f32 v[48:49], v[48:49], v[106:107]
	v_pk_mul_f32 v[64:65], v[64:65], v[106:107]

.LBB0_551:
	s_add_i32 s20, s25, 0x8000
	v_lshl_add_u64 v[86:87], s[16:17], 0, v[170:171]
	s_mov_b32 m0, s20
	s_nop 0
	global_load_lds_dwordx4 v[86:87], off
	ds_read_b128 v[106:109], v200 offset:49152
	ds_read_b128 v[102:105], v199 offset:49152
	ds_read_b128 v[130:133], v199 offset:53248
	ds_read_b128 v[134:137], v200 offset:53248
	s_mov_b32 m0, s25
	s_waitcnt lgkmcnt(0)
	v_mfma_f32_32x32x64_f8f6f4 v[86:101], v[102:109], v[154:161], 0
	s_nop 0
	v_exp_f32_e32 v66, v66
	v_exp_f32_e32 v67, v67
	v_exp_f32_e32 v68, v68
	v_exp_f32_e32 v69, v69
	ds_read_b128 v[102:105], v197 offset:49152
	ds_read_b128 v[106:109], v198 offset:49152
	v_mfma_f32_32x32x64_f8f6f4 v[114:129], v[130:137], v[154:161], 0
	ds_read_b128 v[204:207], v197 offset:53248
	ds_read_b128 v[208:211], v198 offset:53248
	v_exp_f32_e32 v70, v70
	v_exp_f32_e32 v71, v71
	v_exp_f32_e32 v72, v72
	v_exp_f32_e32 v73, v73
	s_waitcnt lgkmcnt(0)
	v_mfma_f32_32x32x64_f8f6f4 v[86:101], v[102:109], v[146:153], v[86:101]
	v_exp_f32_e32 v74, v74
	v_exp_f32_e32 v75, v75
	v_exp_f32_e32 v76, v76
	v_exp_f32_e32 v77, v77
	v_mfma_f32_32x32x64_f8f6f4 v[114:129], v[204:211], v[146:153], v[114:129]
	ds_read_b64_tr_b8 v[102:103], v195 offset:0
	ds_read_b64_tr_b8 v[104:105], v195 offset:0x800
	ds_read_b64_tr_b8 v[106:107], v195 offset:0x1000
	v_exp_f32_e32 v78, v78
	v_exp_f32_e32 v79, v79
	ds_read_b64_tr_b8 v[108:109], v195 offset:0x1800
	v_cvt_pk_fp8_f32 v130, v82, v83
	v_exp_f32_e32 v80, v80
	v_exp_f32_e32 v81, v81
	v_cvt_pk_fp8_f32 v134, v66, v67
	v_cvt_pk_fp8_f32 v131, v176, v177
	v_cvt_pk_fp8_f32 v135, v70, v71
	v_cvt_pk_fp8_f32 v132, v172, v173
	v_cvt_pk_fp8_f32 v136, v74, v75
	v_cvt_pk_fp8_f32 v133, v144, v145
	v_cvt_pk_fp8_f32 v137, v78, v79
	ds_read_b64_tr_b8 v[206:207], v196 offset:0
	ds_read_b64_tr_b8 v[208:209], v196 offset:0x800
	ds_read_b64_tr_b8 v[210:211], v196 offset:0x1000
	ds_read_b64_tr_b8 v[212:213], v196 offset:0x1800
	v_cvt_pk_fp8_f32 v130, v84, v85 op_sel:[0,0,1]
	v_cvt_pk_fp8_f32 v134, v68, v69 op_sel:[0,0,1]
	v_cvt_pk_fp8_f32 v131, v174, v175 op_sel:[0,0,1]
	v_cvt_pk_fp8_f32 v135, v72, v73 op_sel:[0,0,1]
	v_cvt_pk_fp8_f32 v132, v140, v141 op_sel:[0,0,1]
	v_cvt_pk_fp8_f32 v136, v76, v77 op_sel:[0,0,1]
	v_cvt_pk_fp8_f32 v133, v142, v143 op_sel:[0,0,1]
	v_cvt_pk_fp8_f32 v137, v80, v81 op_sel:[0,0,1]
	s_waitcnt lgkmcnt(4)
	v_pk_add_f32 v[82:83], v[82:83], v[84:85]
	v_mfma_f32_32x32x64_f8f6f4 v[2:17], v[130:137], v[102:109], v[2:17]
	ds_read_b64_tr_b8 v[214:215], v194 offset:0
	ds_read_b64_tr_b8 v[216:217], v194 offset:0x800
	ds_read_b64_tr_b8 v[218:219], v194 offset:0x1000
	ds_read_b64_tr_b8 v[220:221], v194 offset:0x1800
	s_waitcnt lgkmcnt(4)
	s_nop 0
	v_max_f32_e32 v102, v86, v87
	v_max3_f32 v102, v102, v88, v89
	v_max3_f32 v102, v102, v90, v91
	v_max3_f32 v102, v102, v92, v93
	v_max3_f32 v102, v102, v94, v95
	v_max3_f32 v102, v102, v96, v97
	v_max3_f32 v102, v102, v98, v99
	v_max3_f32 v102, v102, v100, v101
	v_max3_f32 v102, v102, v114, v115
	v_max3_f32 v102, v102, v116, v117
	v_max3_f32 v102, v102, v118, v119
	v_max3_f32 v102, v102, v120, v121
	v_max3_f32 v102, v102, v122, v123
	v_max3_f32 v102, v102, v124, v125
	v_max3_f32 v102, v102, v126, v127
	v_max3_f32 v102, v102, v128, v129
	v_mov_b32_e32 v103, v102
	s_nop 1
	v_permlane32_swap_b32_e32 v102, v103
	v_max_f32_e32 v102, v102, v103
	v_sub_f32_e32 v103, v102, v202
	v_cmp_ge_f32_e32 vcc, s29, v103
	s_cmp_eq_u64 vcc, exec
	v_max_f32_e32 v103, v202, v202
	v_max_f32_e32 v139, v103, v102
	s_cselect_b64 vcc, -1, 0
	v_cndmask_b32_e32 v204, v139, v202, vcc
	v_fma_f32 v138, v204, s33, 4.0
	v_mfma_f32_32x32x64_f8f6f4 v[18:33], v[130:137], v[206:213], v[18:33]
	v_pk_add_f32 v[82:83], v[176:177], v[82:83]
	v_pk_fma_f32 v[110:111], v[98:99], s[4:5], v[138:139] op_sel_hi:[1,0,0]
	v_pk_fma_f32 v[98:99], v[86:87], s[4:5], v[138:139] op_sel_hi:[1,0,0]
	ds_read_b64_tr_b8 v[86:87], v192 offset:0
	v_pk_fma_f32 v[112:113], v[100:101], s[4:5], v[138:139] op_sel_hi:[1,0,0]
	v_pk_fma_f32 v[100:101], v[88:89], s[4:5], v[138:139] op_sel_hi:[1,0,0]
	ds_read_b64_tr_b8 v[88:89], v192 offset:0x800
	v_pk_fma_f32 v[102:103], v[90:91], s[4:5], v[138:139] op_sel_hi:[1,0,0]
	ds_read_b64_tr_b8 v[90:91], v192 offset:0x1000
	v_pk_fma_f32 v[108:109], v[96:97], s[4:5], v[138:139] op_sel_hi:[1,0,0]
	v_pk_fma_f32 v[106:107], v[94:95], s[4:5], v[138:139] op_sel_hi:[1,0,0]
	v_pk_fma_f32 v[104:105], v[92:93], s[4:5], v[138:139] op_sel_hi:[1,0,0]
	v_pk_fma_f32 v[128:129], v[128:129], s[4:5], v[138:139] op_sel_hi:[1,0,0]
	v_pk_fma_f32 v[126:127], v[126:127], s[4:5], v[138:139] op_sel_hi:[1,0,0]
	v_pk_fma_f32 v[124:125], v[124:125], s[4:5], v[138:139] op_sel_hi:[1,0,0]
	v_pk_fma_f32 v[122:123], v[122:123], s[4:5], v[138:139] op_sel_hi:[1,0,0]
	v_pk_fma_f32 v[120:121], v[120:121], s[4:5], v[138:139] op_sel_hi:[1,0,0]
	v_pk_fma_f32 v[118:119], v[118:119], s[4:5], v[138:139] op_sel_hi:[1,0,0]
	v_pk_fma_f32 v[116:117], v[116:117], s[4:5], v[138:139] op_sel_hi:[1,0,0]
	v_pk_fma_f32 v[114:115], v[114:115], s[4:5], v[138:139] op_sel_hi:[1,0,0]
	ds_read_b64_tr_b8 v[92:93], v192 offset:0x1800
	s_waitcnt lgkmcnt(4)
	v_pk_add_f32 v[82:83], v[174:175], v[82:83]
	v_mfma_f32_32x32x64_f8f6f4 v[34:49], v[130:137], v[214:221], v[34:49]
	s_waitcnt lgkmcnt(0)
	s_nop 0
	v_exp_f32_e32 v98, v98
	v_exp_f32_e32 v99, v99
	v_exp_f32_e32 v100, v100
	v_exp_f32_e32 v101, v101
	v_mfma_f32_32x32x64_f8f6f4 v[50:65], v[130:137], v[86:93], v[50:65]
	s_barrier
	v_lshl_add_u64 v[86:87], s[16:17], 0, v[168:169]
	global_load_lds_dwordx4 v[86:87], off
	v_pk_add_f32 v[82:83], v[172:173], v[82:83]
	s_nop 0
	v_pk_add_f32 v[82:83], v[140:141], v[82:83]
	s_nop 0
	v_pk_add_f32 v[82:83], v[144:145], v[82:83]
	s_nop 0
	v_pk_add_f32 v[82:83], v[142:143], v[82:83]
	s_nop 0
	v_pk_add_f32 v[66:67], v[82:83], v[66:67]
	s_nop 0
	v_pk_add_f32 v[66:67], v[68:69], v[66:67]
	s_nop 0
	v_pk_add_f32 v[66:67], v[70:71], v[66:67]
	s_nop 0
	v_pk_add_f32 v[66:67], v[72:73], v[66:67]
	s_nop 0
	v_pk_add_f32 v[66:67], v[74:75], v[66:67]
	s_nop 0
	v_pk_add_f32 v[66:67], v[76:77], v[66:67]
	s_nop 0
	v_pk_add_f32 v[66:67], v[78:79], v[66:67]
	s_nop 0
	v_pk_add_f32 v[66:67], v[80:81], v[66:67]
	s_nop 0
	v_pk_add_f32 v[172:173], v[66:67], v[66:67] op_sel:[0,1] op_sel_hi:[1,0]
	v_sub_f32_e32 v66, v202, v139
	v_mul_f32_e32 v66, 0x3e0293ee, v66
	v_exp_f32_e32 v66, v66
	v_mov_b32_e32 v203, v172
	s_nop 1
	v_permlane32_swap_b32_e32 v172, v203
	v_cndmask_b32_e64 v173, v66, 1.0, vcc
	v_cmp_gt_f32_e32 vcc, 1.0, v173
	s_cbranch_vccz .LBB0_555
	s_and_saveexec_b64 s[18:19], s[2:3]
	ds_write_b32 v193, v173 offset:128
	s_or_b64 exec, exec, s[18:19]
	s_waitcnt lgkmcnt(0)
	s_nop 15
	s_nop 7
	ds_read2_b32 v[66:67], v191 offset0:32 offset1:33
	ds_read2_b32 v[68:69], v191 offset0:34 offset1:35
	ds_read2_b32 v[70:71], v191 offset0:40 offset1:41
	ds_read2_b32 v[72:73], v191 offset0:42 offset1:43
	s_waitcnt lgkmcnt(0)
	v_pk_mul_f32 v[2:3], v[66:67], v[2:3]
	v_pk_mul_f32 v[18:19], v[66:67], v[18:19]
	v_pk_mul_f32 v[34:35], v[66:67], v[34:35]
	v_pk_mul_f32 v[50:51], v[66:67], v[50:51]
	v_pk_mul_f32 v[4:5], v[4:5], v[68:69]
	v_pk_mul_f32 v[20:21], v[20:21], v[68:69]
	v_pk_mul_f32 v[36:37], v[36:37], v[68:69]
	v_pk_mul_f32 v[52:53], v[52:53], v[68:69]
	v_pk_mul_f32 v[6:7], v[6:7], v[70:71]
	v_pk_mul_f32 v[22:23], v[22:23], v[70:71]
	v_pk_mul_f32 v[38:39], v[38:39], v[70:71]
	v_pk_mul_f32 v[54:55], v[54:55], v[70:71]
	v_pk_mul_f32 v[8:9], v[8:9], v[72:73]
	v_pk_mul_f32 v[24:25], v[24:25], v[72:73]
	v_pk_mul_f32 v[40:41], v[40:41], v[72:73]
	ds_read2_b32 v[66:67], v191 offset0:48 offset1:49
	v_pk_mul_f32 v[56:57], v[56:57], v[72:73]
	ds_read2_b32 v[68:69], v191 offset0:50 offset1:51
	ds_read2_b32 v[70:71], v191 offset0:56 offset1:57
	ds_read2_b32 v[72:73], v191 offset0:58 offset1:59
	s_waitcnt lgkmcnt(0)
	v_pk_mul_f32 v[10:11], v[10:11], v[66:67]
	v_pk_mul_f32 v[26:27], v[26:27], v[66:67]
	v_pk_mul_f32 v[42:43], v[42:43], v[66:67]
	v_pk_mul_f32 v[58:59], v[58:59], v[66:67]
	v_pk_mul_f32 v[12:13], v[12:13], v[68:69]
	v_pk_mul_f32 v[28:29], v[28:29], v[68:69]
	v_pk_mul_f32 v[44:45], v[44:45], v[68:69]
	v_pk_mul_f32 v[60:61], v[60:61], v[68:69]
	v_pk_mul_f32 v[14:15], v[14:15], v[70:71]
	v_pk_mul_f32 v[30:31], v[30:31], v[70:71]
	v_pk_mul_f32 v[46:47], v[46:47], v[70:71]
	v_pk_mul_f32 v[62:63], v[62:63], v[70:71]
	v_pk_mul_f32 v[16:17], v[16:17], v[72:73]
	v_pk_mul_f32 v[32:33], v[32:33], v[72:73]
	v_pk_mul_f32 v[48:49], v[48:49], v[72:73]
	v_pk_mul_f32 v[64:65], v[64:65], v[72:73]
.LBB0_555:
	s_add_i32 s18, s42, 1
	s_cmp_lt_u32 s18, s40
	s_cselect_b32 s18, 0, s40
	s_cselect_b32 s19, s39, 0
	s_lshl_b32 s18, s18, 6
	s_ashr_i32 s23, s19, 31
	s_sub_i32 s18, s22, s18
	s_add_u32 s18, s18, s19
	s_addc_u32 s19, 0, s23
	v_mov_b32_e32 v205, s41
	s_waitcnt vmcnt(1)
	v_mad_u64_u32 v[66:67], s[44:45], s18, v205, v[164:165]
	s_mul_i32 s19, s19, s41
	s_add_i32 s23, s25, 0xc000
	s_barrier
	v_add_u32_e32 v67, s19, v67
	s_mov_b32 m0, s23
	v_exp_f32_e32 v178, v106
	global_load_lds_dwordx4 v[66:67], off
	v_exp_f32_e32 v174, v102
	v_exp_f32_e32 v175, v103
	v_exp_f32_e32 v176, v104
	v_exp_f32_e32 v177, v105
	v_exp_f32_e32 v179, v107
	v_exp_f32_e32 v180, v108
	v_exp_f32_e32 v181, v109
	v_exp_f32_e32 v110, v110
	v_exp_f32_e32 v111, v111
	v_exp_f32_e32 v112, v112
	v_exp_f32_e32 v113, v113
	ds_read_b128 v[86:89], v200 offset:32768
	ds_read_b128 v[82:85], v199 offset:32768
	ds_read_b128 v[90:93], v199 offset:36864
	ds_read_b128 v[94:97], v200 offset:36864
	s_waitcnt lgkmcnt(0)
	v_mfma_f32_32x32x64_f8f6f4 v[66:81], v[82:89], v[154:161], 0
	ds_read_b128 v[82:85], v197 offset:32768
	ds_read_b128 v[86:89], v198 offset:32768
	v_exp_f32_e32 v114, v114
	v_exp_f32_e32 v115, v115
	v_exp_f32_e32 v116, v116
	v_exp_f32_e32 v117, v117
	v_mfma_f32_32x32x64_f8f6f4 v[130:145], v[90:97], v[154:161], 0
	ds_read_b128 v[90:93], v197 offset:36864
	ds_read_b128 v[94:97], v198 offset:36864
	v_exp_f32_e32 v118, v118
	v_exp_f32_e32 v119, v119
	v_exp_f32_e32 v120, v120
	v_exp_f32_e32 v121, v121
	s_waitcnt lgkmcnt(0)
	v_mfma_f32_32x32x64_f8f6f4 v[66:81], v[82:89], v[146:153], v[66:81]
	v_exp_f32_e32 v122, v122
	v_exp_f32_e32 v123, v123
	v_exp_f32_e32 v124, v124
	v_exp_f32_e32 v125, v125
	v_mfma_f32_32x32x64_f8f6f4 v[130:145], v[90:97], v[146:153], v[130:145]
	ds_read_b64_tr_b8 v[82:83], v190 offset:0
	ds_read_b64_tr_b8 v[84:85], v190 offset:0x800
	ds_read_b64_tr_b8 v[86:87], v190 offset:0x1000
	v_exp_f32_e32 v126, v126
	v_exp_f32_e32 v127, v127
	ds_read_b64_tr_b8 v[88:89], v190 offset:0x1800
	v_cvt_pk_fp8_f32 v102, v98, v99
	v_exp_f32_e32 v128, v128
	v_exp_f32_e32 v129, v129
	v_cvt_pk_fp8_f32 v106, v114, v115
	v_cvt_pk_fp8_f32 v103, v174, v175
	v_cvt_pk_fp8_f32 v107, v118, v119
	v_cvt_pk_fp8_f32 v104, v178, v179
	v_cvt_pk_fp8_f32 v108, v122, v123
	v_cvt_pk_fp8_f32 v105, v110, v111
	v_cvt_pk_fp8_f32 v109, v126, v127
	ds_read_b64_tr_b8 v[90:91], v189 offset:0
	ds_read_b64_tr_b8 v[92:93], v189 offset:0x800
	ds_read_b64_tr_b8 v[94:95], v189 offset:0x1000
	ds_read_b64_tr_b8 v[96:97], v189 offset:0x1800
	v_cvt_pk_fp8_f32 v102, v100, v101 op_sel:[0,0,1]
	v_cvt_pk_fp8_f32 v106, v116, v117 op_sel:[0,0,1]
	v_cvt_pk_fp8_f32 v103, v176, v177 op_sel:[0,0,1]
	v_cvt_pk_fp8_f32 v107, v120, v121 op_sel:[0,0,1]
	v_cvt_pk_fp8_f32 v104, v180, v181 op_sel:[0,0,1]
	v_cvt_pk_fp8_f32 v108, v124, v125 op_sel:[0,0,1]
	v_cvt_pk_fp8_f32 v105, v112, v113 op_sel:[0,0,1]
	v_cvt_pk_fp8_f32 v109, v128, v129 op_sel:[0,0,1]
	s_waitcnt lgkmcnt(4)
	s_mov_b32 m0, s43
	v_mfma_f32_32x32x64_f8f6f4 v[2:17], v[102:109], v[82:89], v[2:17]
	ds_read_b64_tr_b8 v[206:207], v188 offset:0
	ds_read_b64_tr_b8 v[208:209], v188 offset:0x800
	ds_read_b64_tr_b8 v[210:211], v188 offset:0x1000
	ds_read_b64_tr_b8 v[212:213], v188 offset:0x1800
	s_waitcnt lgkmcnt(4)
	s_nop 0
	v_max_f32_e32 v82, v66, v67
	v_max3_f32 v82, v82, v68, v69
	v_max3_f32 v82, v82, v70, v71
	v_max3_f32 v82, v82, v72, v73
	v_max3_f32 v82, v82, v74, v75
	v_max3_f32 v82, v82, v76, v77
	v_max3_f32 v82, v82, v78, v79
	v_max3_f32 v82, v82, v80, v81
	v_max3_f32 v82, v82, v130, v131
	v_max3_f32 v82, v82, v132, v133
	v_max3_f32 v82, v82, v134, v135
	v_max3_f32 v82, v82, v136, v137
	v_max3_f32 v82, v82, v138, v139
	v_max3_f32 v82, v82, v140, v141
	v_max3_f32 v82, v82, v142, v143
	v_max3_f32 v82, v82, v144, v145
	v_mov_b32_e32 v83, v82
	s_nop 1
	v_permlane32_swap_b32_e32 v82, v83
	v_max_f32_e32 v82, v82, v83
	v_sub_f32_e32 v83, v82, v204
	v_cmp_ge_f32_e32 vcc, s29, v83
	s_cmp_eq_u64 vcc, exec
	v_max_f32_e32 v83, v204, v204
	v_max_f32_e32 v215, v83, v82
	s_cselect_b64 vcc, -1, 0
	v_cndmask_b32_e32 v202, v215, v204, vcc
	v_fma_f32 v214, v202, s33, 4.0
	v_mfma_f32_32x32x64_f8f6f4 v[18:33], v[102:109], v[90:97], v[18:33]
	v_pk_add_f32 v[98:99], v[98:99], v[100:101]
	v_pk_fma_f32 v[82:83], v[66:67], s[4:5], v[214:215] op_sel_hi:[1,0,0]
	v_pk_fma_f32 v[66:67], v[130:131], s[4:5], v[214:215] op_sel_hi:[1,0,0]
	ds_read_b64_tr_b8 v[130:131], v187 offset:0
	v_pk_fma_f32 v[84:85], v[68:69], s[4:5], v[214:215] op_sel_hi:[1,0,0]
	v_pk_fma_f32 v[68:69], v[132:133], s[4:5], v[214:215] op_sel_hi:[1,0,0]
	ds_read_b64_tr_b8 v[132:133], v187 offset:0x800
	v_pk_fma_f32 v[86:87], v[70:71], s[4:5], v[214:215] op_sel_hi:[1,0,0]
	v_pk_fma_f32 v[70:71], v[134:135], s[4:5], v[214:215] op_sel_hi:[1,0,0]
	ds_read_b64_tr_b8 v[134:135], v187 offset:0x1000
	v_pk_fma_f32 v[96:97], v[80:81], s[4:5], v[214:215] op_sel_hi:[1,0,0]
	v_pk_fma_f32 v[94:95], v[78:79], s[4:5], v[214:215] op_sel_hi:[1,0,0]
	v_pk_fma_f32 v[92:93], v[76:77], s[4:5], v[214:215] op_sel_hi:[1,0,0]
	v_pk_fma_f32 v[90:91], v[74:75], s[4:5], v[214:215] op_sel_hi:[1,0,0]
	v_pk_fma_f32 v[88:89], v[72:73], s[4:5], v[214:215] op_sel_hi:[1,0,0]
	v_pk_fma_f32 v[80:81], v[144:145], s[4:5], v[214:215] op_sel_hi:[1,0,0]
	v_pk_fma_f32 v[78:79], v[142:143], s[4:5], v[214:215] op_sel_hi:[1,0,0]
	v_pk_fma_f32 v[76:77], v[140:141], s[4:5], v[214:215] op_sel_hi:[1,0,0]
	v_pk_fma_f32 v[74:75], v[138:139], s[4:5], v[214:215] op_sel_hi:[1,0,0]
	v_pk_fma_f32 v[72:73], v[136:137], s[4:5], v[214:215] op_sel_hi:[1,0,0]
	ds_read_b64_tr_b8 v[136:137], v187 offset:0x1800
	s_waitcnt lgkmcnt(4)
	v_pk_add_f32 v[98:99], v[98:99], v[174:175]
	v_mfma_f32_32x32x64_f8f6f4 v[34:49], v[102:109], v[206:213], v[34:49]
	s_waitcnt lgkmcnt(0)
	s_nop 0
	v_exp_f32_e32 v82, v82
	v_exp_f32_e32 v83, v83
	v_exp_f32_e32 v84, v84
	v_exp_f32_e32 v85, v85
	v_mfma_f32_32x32x64_f8f6f4 v[50:65], v[102:109], v[130:137], v[50:65]
	v_mad_u64_u32 v[102:103], s[44:45], s18, v205, v[166:167]
	s_barrier
	v_add_u32_e32 v103, s19, v103
	global_load_lds_dwordx4 v[102:103], off
	v_pk_add_f32 v[98:99], v[176:177], v[98:99]
	s_nop 0
	v_pk_add_f32 v[98:99], v[178:179], v[98:99]
	s_nop 0
	v_pk_add_f32 v[98:99], v[180:181], v[98:99]
	s_nop 0
	v_pk_add_f32 v[98:99], v[110:111], v[98:99]
	s_nop 0
	v_pk_add_f32 v[98:99], v[112:113], v[98:99]
	s_nop 0
	v_pk_add_f32 v[98:99], v[98:99], v[114:115]
	s_nop 0
	v_pk_add_f32 v[98:99], v[116:117], v[98:99]
	s_nop 0
	v_pk_add_f32 v[98:99], v[118:119], v[98:99]
	s_nop 0
	v_pk_add_f32 v[98:99], v[120:121], v[98:99]
	s_nop 0
	v_pk_add_f32 v[98:99], v[122:123], v[98:99]
	s_nop 0
	v_pk_add_f32 v[98:99], v[124:125], v[98:99]
	s_nop 0
	v_pk_add_f32 v[98:99], v[126:127], v[98:99]
	s_nop 0
	v_pk_add_f32 v[98:99], v[128:129], v[98:99]
	s_nop 0
	v_pk_add_f32 v[98:99], v[98:99], v[98:99] op_sel:[0,1] op_sel_hi:[1,0]
	s_nop 0
	v_sub_f32_e32 v99, v204, v215
	v_mul_f32_e32 v99, 0x3e0293ee, v99
	v_exp_f32_e32 v100, v99
	v_mov_b32_e32 v99, v98
	s_nop 1
	v_permlane32_swap_b32_e32 v98, v99
	v_cndmask_b32_e64 v178, v100, 1.0, vcc
	v_cmp_gt_f32_e32 vcc, 1.0, v178
	s_cbranch_vccz .LBB0_559
	s_and_saveexec_b64 s[18:19], s[2:3]
	ds_write_b32 v193, v178 offset:128
	s_or_b64 exec, exec, s[18:19]
	s_waitcnt lgkmcnt(0)
	s_nop 15
	s_nop 7
	ds_read2_b32 v[100:101], v191 offset0:32 offset1:33
	ds_read2_b32 v[102:103], v191 offset0:34 offset1:35
	ds_read2_b32 v[104:105], v191 offset0:40 offset1:41
	ds_read2_b32 v[106:107], v191 offset0:42 offset1:43
	s_waitcnt lgkmcnt(0)
	v_pk_mul_f32 v[2:3], v[100:101], v[2:3]
	v_pk_mul_f32 v[18:19], v[100:101], v[18:19]
	v_pk_mul_f32 v[34:35], v[100:101], v[34:35]
	v_pk_mul_f32 v[50:51], v[100:101], v[50:51]
	v_pk_mul_f32 v[4:5], v[4:5], v[102:103]
	v_pk_mul_f32 v[20:21], v[20:21], v[102:103]
	v_pk_mul_f32 v[36:37], v[36:37], v[102:103]
	v_pk_mul_f32 v[52:53], v[52:53], v[102:103]
	v_pk_mul_f32 v[6:7], v[6:7], v[104:105]
	v_pk_mul_f32 v[22:23], v[22:23], v[104:105]
	v_pk_mul_f32 v[38:39], v[38:39], v[104:105]
	v_pk_mul_f32 v[54:55], v[54:55], v[104:105]
	v_pk_mul_f32 v[8:9], v[8:9], v[106:107]
	v_pk_mul_f32 v[24:25], v[24:25], v[106:107]
	v_pk_mul_f32 v[40:41], v[40:41], v[106:107]
	ds_read2_b32 v[100:101], v191 offset0:48 offset1:49
	v_pk_mul_f32 v[56:57], v[56:57], v[106:107]
	ds_read2_b32 v[102:103], v191 offset0:50 offset1:51
	ds_read2_b32 v[104:105], v191 offset0:56 offset1:57
	ds_read2_b32 v[106:107], v191 offset0:58 offset1:59
	s_waitcnt lgkmcnt(0)
	v_pk_mul_f32 v[10:11], v[10:11], v[100:101]
	v_pk_mul_f32 v[26:27], v[26:27], v[100:101]
	v_pk_mul_f32 v[42:43], v[42:43], v[100:101]
	v_pk_mul_f32 v[58:59], v[58:59], v[100:101]
	v_pk_mul_f32 v[12:13], v[12:13], v[102:103]
	v_pk_mul_f32 v[28:29], v[28:29], v[102:103]
	v_pk_mul_f32 v[44:45], v[44:45], v[102:103]
	v_pk_mul_f32 v[60:61], v[60:61], v[102:103]
	v_pk_mul_f32 v[14:15], v[14:15], v[104:105]
	v_pk_mul_f32 v[30:31], v[30:31], v[104:105]
	v_pk_mul_f32 v[46:47], v[46:47], v[104:105]
	v_pk_mul_f32 v[62:63], v[62:63], v[104:105]
	v_pk_mul_f32 v[16:17], v[16:17], v[106:107]
	v_pk_mul_f32 v[32:33], v[32:33], v[106:107]
	v_pk_mul_f32 v[48:49], v[48:49], v[106:107]
	v_pk_mul_f32 v[64:65], v[64:65], v[106:107]

.LBB0_561:
	ds_read_b128 v[90:93], v200 offset:49152
	ds_read_b128 v[86:89], v199 offset:49152
	ds_read_b128 v[130:133], v199 offset:53248
	ds_read_b128 v[134:137], v200 offset:53248
	v_pk_add_f32 v[94:95], v[82:83], v[84:85]
	s_waitcnt lgkmcnt(0)
	v_mfma_f32_32x32x64_f8f6f4 v[114:129], v[86:93], v[154:161], 0
	s_nop 0
	v_exp_f32_e32 v66, v66
	v_exp_f32_e32 v67, v67
	v_exp_f32_e32 v68, v68
	v_exp_f32_e32 v69, v69
	ds_read_b128 v[86:89], v197 offset:49152
	ds_read_b128 v[90:93], v198 offset:49152
	v_mfma_f32_32x32x64_f8f6f4 v[98:113], v[130:137], v[154:161], 0
	ds_read_b128 v[130:133], v197 offset:53248
	ds_read_b128 v[134:137], v198 offset:53248
	v_exp_f32_e32 v70, v70
	v_exp_f32_e32 v71, v71
	v_exp_f32_e32 v72, v72
	v_exp_f32_e32 v73, v73
	v_pk_add_f32 v[94:95], v[94:95], v[176:177]
	s_waitcnt lgkmcnt(0)
	v_mfma_f32_32x32x64_f8f6f4 v[114:129], v[86:93], v[146:153], v[114:129]
	v_pk_add_f32 v[94:95], v[94:95], v[174:175]
	v_exp_f32_e32 v74, v74
	v_exp_f32_e32 v75, v75
	v_exp_f32_e32 v76, v76
	v_exp_f32_e32 v77, v77
	v_pk_add_f32 v[86:87], v[94:95], v[172:173]
	v_mfma_f32_32x32x64_f8f6f4 v[98:113], v[130:137], v[146:153], v[98:113]
	v_mov_b32_e32 v134, v163
	v_pk_add_f32 v[86:87], v[86:87], v[140:141]
	v_cvt_pk_fp8_f32 v134, v66, v67
	v_pk_add_f32 v[86:87], v[86:87], v[144:145]
	v_mov_b32_e32 v135, v163
	v_exp_f32_e32 v78, v78
	v_exp_f32_e32 v79, v79
	v_pk_add_f32 v[86:87], v[86:87], v[142:143]
	v_cvt_pk_fp8_f32 v135, v70, v71
	v_pk_add_f32 v[86:87], v[86:87], v[66:67]
	v_mov_b32_e32 v136, v163
	ds_read_b64_tr_b8 v[66:67], v195 offset:0
	v_pk_add_f32 v[86:87], v[68:69], v[86:87]
	v_cvt_pk_fp8_f32 v134, v68, v69 op_sel:[0,0,1]
	v_cvt_pk_fp8_f32 v136, v74, v75
	ds_read_b64_tr_b8 v[68:69], v195 offset:0x800
	v_pk_add_f32 v[86:87], v[70:71], v[86:87]
	v_mov_b32_e32 v137, v163
	ds_read_b64_tr_b8 v[70:71], v195 offset:0x1000
	v_exp_f32_e32 v80, v80
	v_exp_f32_e32 v81, v81
	v_pk_add_f32 v[86:87], v[72:73], v[86:87]
	v_mov_b32_e32 v130, v163
	v_mov_b32_e32 v131, v163
	v_cvt_pk_fp8_f32 v135, v72, v73 op_sel:[0,0,1]
	v_mov_b32_e32 v132, v163
	v_mov_b32_e32 v133, v163
	v_cvt_pk_fp8_f32 v137, v78, v79
	ds_read_b64_tr_b8 v[72:73], v195 offset:0x1800
	v_pk_add_f32 v[86:87], v[74:75], v[86:87]
	v_cvt_pk_fp8_f32 v130, v82, v83
	v_cvt_pk_fp8_f32 v131, v176, v177
	v_cvt_pk_fp8_f32 v132, v172, v173
	v_cvt_pk_fp8_f32 v133, v144, v145
	ds_read_b64_tr_b8 v[74:75], v196 offset:0
	v_pk_add_f32 v[86:87], v[76:77], v[86:87]
	v_cvt_pk_fp8_f32 v136, v76, v77 op_sel:[0,0,1]
	ds_read_b64_tr_b8 v[76:77], v196 offset:0x800
	v_pk_add_f32 v[86:87], v[78:79], v[86:87]
	ds_read_b64_tr_b8 v[78:79], v196 offset:0x1000
	v_cvt_pk_fp8_f32 v137, v80, v81 op_sel:[0,0,1]
	v_pk_add_f32 v[86:87], v[80:81], v[86:87]
	ds_read_b64_tr_b8 v[80:81], v196 offset:0x1800
	v_cvt_pk_fp8_f32 v130, v84, v85 op_sel:[0,0,1]
	v_cvt_pk_fp8_f32 v131, v174, v175 op_sel:[0,0,1]
	v_cvt_pk_fp8_f32 v132, v140, v141 op_sel:[0,0,1]
	v_cvt_pk_fp8_f32 v133, v142, v143 op_sel:[0,0,1]
	s_waitcnt lgkmcnt(4)
	v_pk_add_f32 v[138:139], v[86:87], v[86:87] op_sel:[0,1] op_sel_hi:[1,0]
	v_mfma_f32_32x32x64_f8f6f4 v[2:17], v[130:137], v[66:73], v[2:17]
	ds_read_b64_tr_b8 v[140:141], v194 offset:0
	ds_read_b64_tr_b8 v[142:143], v194 offset:0x800
	ds_read_b64_tr_b8 v[144:145], v194 offset:0x1000
	ds_read_b64_tr_b8 v[146:147], v194 offset:0x1800
	s_waitcnt lgkmcnt(4)
	s_nop 0
	v_max_f32_e32 v66, v114, v115
	v_max3_f32 v66, v66, v116, v117
	v_max3_f32 v66, v66, v118, v119
	v_max3_f32 v66, v66, v120, v121
	v_max3_f32 v66, v66, v122, v123
	v_max3_f32 v66, v66, v124, v125
	v_max3_f32 v66, v66, v126, v127
	v_max3_f32 v66, v66, v128, v129
	v_max3_f32 v66, v66, v98, v99
	v_max3_f32 v66, v66, v100, v101
	v_max3_f32 v66, v66, v102, v103
	v_max3_f32 v66, v66, v104, v105
	v_max3_f32 v66, v66, v106, v107
	v_max3_f32 v66, v66, v108, v109
	v_max3_f32 v66, v66, v110, v111
	v_max3_f32 v66, v66, v112, v113
	v_mov_b32_e32 v67, v66
	s_nop 1
	v_permlane32_swap_b32_e32 v66, v67
	v_max_f32_e32 v66, v66, v67
	v_sub_f32_e32 v67, v66, v202
	v_cmp_ge_f32_e32 vcc, s29, v67
	s_cmp_eq_u64 vcc, exec
	v_max_f32_e32 v66, v202, v66
	s_cselect_b64 vcc, -1, 0
	v_sub_f32_e32 v67, v202, v66
	v_cndmask_b32_e32 v66, v66, v202, vcc
	v_mul_f32_e32 v83, 0x3e0293ee, v67
	v_fma_f32 v82, v66, s33, 4.0
	v_mfma_f32_32x32x64_f8f6f4 v[18:33], v[130:137], v[74:81], v[18:33]
	v_mov_b32_e32 v139, v138
	v_pk_fma_f32 v[84:85], v[100:101], s[4:5], v[82:83] op_sel_hi:[1,0,0]
	ds_read_b64_tr_b8 v[100:101], v192 offset:0
	v_pk_fma_f32 v[66:67], v[114:115], s[4:5], v[82:83] op_sel_hi:[1,0,0]
	v_exp_f32_e32 v114, v83
	v_pk_fma_f32 v[86:87], v[102:103], s[4:5], v[82:83] op_sel_hi:[1,0,0]
	ds_read_b64_tr_b8 v[102:103], v192 offset:0x800
	v_pk_fma_f32 v[88:89], v[104:105], s[4:5], v[82:83] op_sel_hi:[1,0,0]
	ds_read_b64_tr_b8 v[104:105], v192 offset:0x1000
	v_pk_fma_f32 v[80:81], v[128:129], s[4:5], v[82:83] op_sel_hi:[1,0,0]
	v_pk_fma_f32 v[78:79], v[126:127], s[4:5], v[82:83] op_sel_hi:[1,0,0]
	v_pk_fma_f32 v[76:77], v[124:125], s[4:5], v[82:83] op_sel_hi:[1,0,0]
	v_pk_fma_f32 v[74:75], v[122:123], s[4:5], v[82:83] op_sel_hi:[1,0,0]
	v_pk_fma_f32 v[72:73], v[120:121], s[4:5], v[82:83] op_sel_hi:[1,0,0]
	v_pk_fma_f32 v[70:71], v[118:119], s[4:5], v[82:83] op_sel_hi:[1,0,0]
	v_pk_fma_f32 v[68:69], v[116:117], s[4:5], v[82:83] op_sel_hi:[1,0,0]
	v_pk_fma_f32 v[96:97], v[112:113], s[4:5], v[82:83] op_sel_hi:[1,0,0]
	v_pk_fma_f32 v[94:95], v[110:111], s[4:5], v[82:83] op_sel_hi:[1,0,0]
	v_pk_fma_f32 v[92:93], v[108:109], s[4:5], v[82:83] op_sel_hi:[1,0,0]
	v_pk_fma_f32 v[90:91], v[106:107], s[4:5], v[82:83] op_sel_hi:[1,0,0]
	v_pk_fma_f32 v[82:83], v[98:99], s[4:5], v[82:83] op_sel_hi:[1,0,0]
	ds_read_b64_tr_b8 v[106:107], v192 offset:0x1800
	s_waitcnt lgkmcnt(4)
	v_cndmask_b32_e64 v98, v114, 1.0, vcc
	v_mfma_f32_32x32x64_f8f6f4 v[34:49], v[130:137], v[140:147], v[34:49]
	s_waitcnt lgkmcnt(0)
	v_permlane32_swap_b32_e32 v138, v139
	v_exp_f32_e32 v66, v66
	v_exp_f32_e32 v67, v67
	v_exp_f32_e32 v68, v68
	v_exp_f32_e32 v69, v69
	v_cmp_gt_f32_e32 vcc, 1.0, v98
	v_mfma_f32_32x32x64_f8f6f4 v[50:65], v[130:137], v[100:107], v[50:65]
	s_cbranch_vccz .LBB0_565
	s_and_saveexec_b64 s[16:17], s[2:3]
	ds_write_b32 v193, v98 offset:128
	s_or_b64 exec, exec, s[16:17]
	s_waitcnt lgkmcnt(0)
	s_nop 15
	s_nop 7
	ds_read2_b32 v[100:101], v191 offset0:32 offset1:33
	ds_read2_b32 v[102:103], v191 offset0:34 offset1:35
	ds_read2_b32 v[104:105], v191 offset0:40 offset1:41
	ds_read2_b32 v[106:107], v191 offset0:42 offset1:43
	s_waitcnt lgkmcnt(0)
	v_pk_mul_f32 v[2:3], v[100:101], v[2:3]
	v_pk_mul_f32 v[18:19], v[100:101], v[18:19]
	v_pk_mul_f32 v[34:35], v[100:101], v[34:35]
	v_pk_mul_f32 v[50:51], v[100:101], v[50:51]
	v_pk_mul_f32 v[4:5], v[4:5], v[102:103]
	v_pk_mul_f32 v[20:21], v[20:21], v[102:103]
	v_pk_mul_f32 v[36:37], v[36:37], v[102:103]
	v_pk_mul_f32 v[52:53], v[52:53], v[102:103]
	v_pk_mul_f32 v[6:7], v[6:7], v[104:105]
	v_pk_mul_f32 v[22:23], v[22:23], v[104:105]
	v_pk_mul_f32 v[38:39], v[38:39], v[104:105]
	v_pk_mul_f32 v[54:55], v[54:55], v[104:105]
	v_pk_mul_f32 v[8:9], v[8:9], v[106:107]
	v_pk_mul_f32 v[24:25], v[24:25], v[106:107]
	v_pk_mul_f32 v[40:41], v[40:41], v[106:107]
	ds_read2_b32 v[100:101], v191 offset0:48 offset1:49
	v_pk_mul_f32 v[56:57], v[56:57], v[106:107]
	ds_read2_b32 v[102:103], v191 offset0:50 offset1:51
	ds_read2_b32 v[104:105], v191 offset0:56 offset1:57
	ds_read2_b32 v[106:107], v191 offset0:58 offset1:59
	s_waitcnt lgkmcnt(0)
	v_pk_mul_f32 v[10:11], v[10:11], v[100:101]
	v_pk_mul_f32 v[26:27], v[26:27], v[100:101]
	v_pk_mul_f32 v[42:43], v[42:43], v[100:101]
	v_pk_mul_f32 v[58:59], v[58:59], v[100:101]
	v_pk_mul_f32 v[12:13], v[12:13], v[102:103]
	v_pk_mul_f32 v[28:29], v[28:29], v[102:103]
	v_pk_mul_f32 v[44:45], v[44:45], v[102:103]
	v_pk_mul_f32 v[60:61], v[60:61], v[102:103]
	v_pk_mul_f32 v[14:15], v[14:15], v[104:105]
	v_pk_mul_f32 v[30:31], v[30:31], v[104:105]
	v_pk_mul_f32 v[46:47], v[46:47], v[104:105]
	v_pk_mul_f32 v[62:63], v[62:63], v[104:105]
	v_pk_mul_f32 v[16:17], v[16:17], v[106:107]
	v_pk_mul_f32 v[32:33], v[32:33], v[106:107]
	v_pk_mul_f32 v[48:49], v[48:49], v[106:107]
	v_pk_mul_f32 v[64:65], v[64:65], v[106:107]

.LBB0_1849:
	v_lshl_add_u64 v[186:187], s[0:1], 0, v[180:181]
	s_add_i32 s55, s37, 0x8000
	v_lshl_add_u64 v[86:87], v[186:187], 0, s[8:9]
	s_mov_b32 m0, s55
	v_lshl_add_u64 v[188:189], s[0:1], 0, v[176:177]
	s_add_i32 s54, s42, s56
	global_load_lds_dwordx4 v[86:87], off
	v_lshl_add_u64 v[86:87], v[188:189], 0, s[10:11]
	s_mov_b32 m0, s54
	s_nop 0
	global_load_lds_dwordx4 v[86:87], off
	ds_read_b128 v[102:105], v209 offset:49152
	ds_read_b128 v[106:109], v210 offset:49152
	ds_read_b128 v[130:133], v211 offset:49152
	ds_read_b128 v[134:137], v212 offset:49152
	v_add_u32_e32 v224, v222, v215
	v_add_u32_e32 v225, v222, v217
	s_waitcnt lgkmcnt(0)
	v_mfma_f32_32x32x64_f8f6f4 v[86:101], v[102:109], v[146:153], 0
	ds_read_b128 v[102:105], v213 offset:49152
	ds_read_b128 v[106:109], v214 offset:49152
	v_exp_f32_e32 v66, v66
	v_exp_f32_e32 v67, v67
	v_exp_f32_e32 v68, v68
	v_mfma_f32_32x32x64_f8f6f4 v[114:129], v[130:137], v[146:153], 0
	ds_read_b128 v[232:235], v207 offset:49152
	ds_read_b128 v[236:239], v208 offset:49152
	v_exp_f32_e32 v69, v69
	v_exp_f32_e32 v70, v70
	v_exp_f32_e32 v71, v71
	s_waitcnt lgkmcnt(0)
	v_mfma_f32_32x32x64_f8f6f4 v[86:101], v[102:109], v[154:161], v[86:101]
	ds_read_b128 v[102:105], v224
	ds_read_b128 v[106:109], v225
	v_exp_f32_e32 v72, v72
	v_exp_f32_e32 v73, v73
	v_exp_f32_e32 v74, v74
	v_add_u32_e32 v226, v223, v215
	v_mfma_f32_32x32x64_f8f6f4 v[114:129], v[232:239], v[154:161], v[114:129]
	v_add_u32_e32 v227, v223, v217
	ds_read_b128 v[232:235], v226
	ds_read_b128 v[236:239], v227
	v_exp_f32_e32 v75, v75
	v_exp_f32_e32 v76, v76
	v_exp_f32_e32 v77, v77
	s_waitcnt lgkmcnt(0)
	v_mfma_f32_32x32x64_f8f6f4 v[86:101], v[102:109], v[162:169], v[86:101]
	v_exp_f32_e32 v78, v78
	v_exp_f32_e32 v79, v79
	v_mfma_f32_32x32x64_f8f6f4 v[114:129], v[232:239], v[162:169], v[114:129]
	ds_read_b64_tr_b8 v[102:103], v206 offset:0
	ds_read_b64_tr_b8 v[104:105], v206 offset:0x800
	ds_read_b64_tr_b8 v[106:107], v206 offset:0x1000
	ds_read_b64_tr_b8 v[108:109], v206 offset:0x1800
	v_cvt_pk_fp8_f32 v130, v82, v83
	v_cvt_pk_fp8_f32 v131, v184, v185
	v_cvt_pk_fp8_f32 v132, v144, v145
	v_cvt_pk_fp8_f32 v134, v66, v67
	v_cvt_pk_fp8_f32 v135, v70, v71
	v_exp_f32_e32 v80, v80
	v_exp_f32_e32 v81, v81
	v_cvt_pk_fp8_f32 v136, v74, v75
	v_cvt_pk_fp8_f32 v133, v142, v143
	v_cvt_pk_fp8_f32 v137, v78, v79
	ds_read_b64_tr_b8 v[232:233], v205 offset:0
	ds_read_b64_tr_b8 v[234:235], v205 offset:0x800
	ds_read_b64_tr_b8 v[236:237], v205 offset:0x1000
	ds_read_b64_tr_b8 v[238:239], v205 offset:0x1800
	v_cvt_pk_fp8_f32 v130, v84, v85 op_sel:[0,0,1]
	v_cvt_pk_fp8_f32 v131, v182, v183 op_sel:[0,0,1]
	v_cvt_pk_fp8_f32 v134, v68, v69 op_sel:[0,0,1]
	v_cvt_pk_fp8_f32 v135, v72, v73 op_sel:[0,0,1]
	v_cvt_pk_fp8_f32 v132, v138, v139 op_sel:[0,0,1]
	v_cvt_pk_fp8_f32 v136, v76, v77 op_sel:[0,0,1]
	v_cvt_pk_fp8_f32 v133, v140, v141 op_sel:[0,0,1]
	v_cvt_pk_fp8_f32 v137, v80, v81 op_sel:[0,0,1]
	s_waitcnt lgkmcnt(4)
	s_mov_b32 m0, s37
	v_mfma_f32_32x32x64_f8f6f4 v[2:17], v[130:137], v[102:109], v[2:17]
	ds_read_b64_tr_b8 v[240:241], v203 offset:0
	ds_read_b64_tr_b8 v[242:243], v203 offset:0x800
	ds_read_b64_tr_b8 v[244:245], v203 offset:0x1000
	ds_read_b64_tr_b8 v[246:247], v203 offset:0x1800
	s_waitcnt lgkmcnt(4)
	s_nop 0
	v_max_f32_e32 v102, v86, v87
	v_max3_f32 v102, v102, v88, v89
	v_max3_f32 v102, v102, v90, v91
	v_max3_f32 v102, v102, v92, v93
	v_max3_f32 v102, v102, v94, v95
	v_max3_f32 v102, v102, v96, v97
	v_max3_f32 v102, v102, v98, v99
	v_max3_f32 v102, v102, v100, v101
	v_max3_f32 v102, v102, v114, v115
	v_max3_f32 v102, v102, v116, v117
	v_max3_f32 v102, v102, v118, v119
	v_max3_f32 v102, v102, v120, v121
	v_max3_f32 v102, v102, v122, v123
	v_max3_f32 v102, v102, v124, v125
	v_max3_f32 v102, v102, v126, v127
	v_max3_f32 v102, v102, v128, v129
	v_mov_b32_e32 v103, v102
	s_nop 1
	v_permlane32_swap_b32_e32 v102, v103
	v_max_f32_e32 v102, v102, v103
	v_sub_f32_e32 v103, v102, v228
	v_cmp_ge_f32_e32 vcc, s46, v103
	s_cmp_eq_u64 vcc, exec
	v_max_f32_e32 v103, v228, v228
	v_max_f32_e32 v192, v103, v102
	s_cselect_b64 vcc, -1, 0
	v_cndmask_b32_e32 v231, v192, v228, vcc
	v_fma_f32 v190, v231, s47, 4.0
	v_mfma_f32_32x32x64_f8f6f4 v[18:33], v[130:137], v[232:239], v[18:33]
	v_pk_add_f32 v[82:83], v[82:83], v[84:85]
	v_pk_fma_f32 v[110:111], v[98:99], s[4:5], v[190:191] op_sel_hi:[1,0,0]
	v_pk_fma_f32 v[98:99], v[86:87], s[4:5], v[190:191] op_sel_hi:[1,0,0]
	ds_read_b64_tr_b8 v[86:87], v202 offset:0
	v_pk_fma_f32 v[112:113], v[100:101], s[4:5], v[190:191] op_sel_hi:[1,0,0]
	v_pk_fma_f32 v[100:101], v[88:89], s[4:5], v[190:191] op_sel_hi:[1,0,0]
	ds_read_b64_tr_b8 v[88:89], v202 offset:0x800
	v_pk_fma_f32 v[102:103], v[90:91], s[4:5], v[190:191] op_sel_hi:[1,0,0]
	ds_read_b64_tr_b8 v[90:91], v202 offset:0x1000
	v_pk_fma_f32 v[108:109], v[96:97], s[4:5], v[190:191] op_sel_hi:[1,0,0]
	v_pk_fma_f32 v[106:107], v[94:95], s[4:5], v[190:191] op_sel_hi:[1,0,0]
	v_pk_fma_f32 v[104:105], v[92:93], s[4:5], v[190:191] op_sel_hi:[1,0,0]
	v_pk_fma_f32 v[128:129], v[128:129], s[4:5], v[190:191] op_sel_hi:[1,0,0]
	v_pk_fma_f32 v[126:127], v[126:127], s[4:5], v[190:191] op_sel_hi:[1,0,0]
	v_pk_fma_f32 v[124:125], v[124:125], s[4:5], v[190:191] op_sel_hi:[1,0,0]
	v_pk_fma_f32 v[122:123], v[122:123], s[4:5], v[190:191] op_sel_hi:[1,0,0]
	v_pk_fma_f32 v[120:121], v[120:121], s[4:5], v[190:191] op_sel_hi:[1,0,0]
	v_pk_fma_f32 v[118:119], v[118:119], s[4:5], v[190:191] op_sel_hi:[1,0,0]
	v_pk_fma_f32 v[116:117], v[116:117], s[4:5], v[190:191] op_sel_hi:[1,0,0]
	v_pk_fma_f32 v[114:115], v[114:115], s[4:5], v[190:191] op_sel_hi:[1,0,0]
	ds_read_b64_tr_b8 v[92:93], v202 offset:0x1800
	s_waitcnt lgkmcnt(4)
	v_lshl_add_u64 v[190:191], s[0:1], 0, v[178:179]
	v_mfma_f32_32x32x64_f8f6f4 v[34:49], v[130:137], v[240:247], v[34:49]
	s_waitcnt lgkmcnt(0)
	v_pk_add_f32 v[82:83], v[184:185], v[82:83]
	v_exp_f32_e32 v98, v98
	v_exp_f32_e32 v99, v99
	v_exp_f32_e32 v100, v100
	v_exp_f32_e32 v101, v101
	v_mfma_f32_32x32x64_f8f6f4 v[50:65], v[130:137], v[86:93], v[50:65]
	s_barrier
	v_lshl_add_u64 v[86:87], v[190:191], 0, s[12:13]
	global_load_lds_dwordx4 v[86:87], off
	v_pk_add_f32 v[82:83], v[182:183], v[82:83]
	s_nop 0
	v_pk_add_f32 v[82:83], v[144:145], v[82:83]
	s_nop 0
	v_pk_add_f32 v[82:83], v[138:139], v[82:83]
	s_nop 0
	v_pk_add_f32 v[82:83], v[142:143], v[82:83]
	s_nop 0
	v_pk_add_f32 v[82:83], v[140:141], v[82:83]
	s_nop 0
	v_pk_add_f32 v[66:67], v[82:83], v[66:67]
	s_nop 0
	v_pk_add_f32 v[66:67], v[68:69], v[66:67]
	s_nop 0
	v_pk_add_f32 v[66:67], v[70:71], v[66:67]
	s_nop 0
	v_pk_add_f32 v[66:67], v[72:73], v[66:67]
	s_nop 0
	v_pk_add_f32 v[66:67], v[74:75], v[66:67]
	s_nop 0
	v_pk_add_f32 v[66:67], v[76:77], v[66:67]
	s_nop 0
	v_pk_add_f32 v[66:67], v[78:79], v[66:67]
	s_nop 0
	v_pk_add_f32 v[66:67], v[80:81], v[66:67]
	s_nop 0
	v_pk_add_f32 v[182:183], v[66:67], v[66:67] op_sel:[0,1] op_sel_hi:[1,0]
	v_sub_f32_e32 v66, v228, v192
	v_mul_f32_e32 v66, 0x3dd53b94, v66
	v_exp_f32_e32 v66, v66
	v_mov_b32_e32 v229, v182
	s_nop 1
	v_permlane32_swap_b32_e32 v182, v229
	v_cndmask_b32_e64 v183, v66, 1.0, vcc
	v_cmp_gt_f32_e32 vcc, 1.0, v183
	s_cbranch_vccz .LBB0_1853
	s_and_saveexec_b64 s[34:35], s[2:3]
	ds_write_b32 v204, v183 offset:128
	s_or_b64 exec, exec, s[34:35]
	s_waitcnt lgkmcnt(0)
	s_nop 15
	s_nop 7
	ds_read2_b32 v[66:67], v201 offset0:32 offset1:33
	ds_read2_b32 v[68:69], v201 offset0:34 offset1:35
	ds_read2_b32 v[70:71], v201 offset0:40 offset1:41
	ds_read2_b32 v[72:73], v201 offset0:42 offset1:43
	s_waitcnt lgkmcnt(0)
	v_pk_mul_f32 v[2:3], v[66:67], v[2:3]
	v_pk_mul_f32 v[18:19], v[66:67], v[18:19]
	v_pk_mul_f32 v[34:35], v[66:67], v[34:35]
	v_pk_mul_f32 v[50:51], v[66:67], v[50:51]
	v_pk_mul_f32 v[4:5], v[4:5], v[68:69]
	v_pk_mul_f32 v[20:21], v[20:21], v[68:69]
	v_pk_mul_f32 v[36:37], v[36:37], v[68:69]
	v_pk_mul_f32 v[52:53], v[52:53], v[68:69]
	v_pk_mul_f32 v[6:7], v[6:7], v[70:71]
	v_pk_mul_f32 v[22:23], v[22:23], v[70:71]
	v_pk_mul_f32 v[38:39], v[38:39], v[70:71]
	v_pk_mul_f32 v[54:55], v[54:55], v[70:71]
	v_pk_mul_f32 v[8:9], v[8:9], v[72:73]
	v_pk_mul_f32 v[24:25], v[24:25], v[72:73]
	v_pk_mul_f32 v[40:41], v[40:41], v[72:73]
	ds_read2_b32 v[66:67], v201 offset0:48 offset1:49
	v_pk_mul_f32 v[56:57], v[56:57], v[72:73]
	ds_read2_b32 v[68:69], v201 offset0:50 offset1:51
	ds_read2_b32 v[70:71], v201 offset0:56 offset1:57
	ds_read2_b32 v[72:73], v201 offset0:58 offset1:59
	s_waitcnt lgkmcnt(0)
	v_pk_mul_f32 v[10:11], v[10:11], v[66:67]
	v_pk_mul_f32 v[26:27], v[26:27], v[66:67]
	v_pk_mul_f32 v[42:43], v[42:43], v[66:67]
	v_pk_mul_f32 v[58:59], v[58:59], v[66:67]
	v_pk_mul_f32 v[12:13], v[12:13], v[68:69]
	v_pk_mul_f32 v[28:29], v[28:29], v[68:69]
	v_pk_mul_f32 v[44:45], v[44:45], v[68:69]
	v_pk_mul_f32 v[60:61], v[60:61], v[68:69]
	v_pk_mul_f32 v[14:15], v[14:15], v[70:71]
	v_pk_mul_f32 v[30:31], v[30:31], v[70:71]
	v_pk_mul_f32 v[46:47], v[46:47], v[70:71]
	v_pk_mul_f32 v[62:63], v[62:63], v[70:71]
	v_pk_mul_f32 v[16:17], v[16:17], v[72:73]
	v_pk_mul_f32 v[32:33], v[32:33], v[72:73]
	v_pk_mul_f32 v[48:49], v[48:49], v[72:73]
	v_pk_mul_f32 v[64:65], v[64:65], v[72:73]
.LBB0_1853:
	s_waitcnt vmcnt(1)
	s_add_i32 s60, s37, 0xc000
	s_barrier
	v_lshl_add_u64 v[66:67], v[186:187], 0, s[14:15]
	s_mov_b32 m0, s60
	s_add_i32 s59, s43, s56
	global_load_lds_dwordx4 v[66:67], off
	v_lshl_add_u64 v[66:67], v[188:189], 0, s[16:17]
	s_mov_b32 m0, s59
	v_exp_f32_e32 v184, v102
	global_load_lds_dwordx4 v[66:67], off
	v_exp_f32_e32 v185, v103
	v_exp_f32_e32 v186, v104
	v_exp_f32_e32 v187, v105
	v_exp_f32_e32 v188, v106
	v_exp_f32_e32 v189, v107
	v_exp_f32_e32 v192, v108
	v_exp_f32_e32 v193, v109
	v_exp_f32_e32 v110, v110
	v_exp_f32_e32 v111, v111
	v_exp_f32_e32 v112, v112
	v_exp_f32_e32 v113, v113
	ds_read_b128 v[82:85], v209 offset:32768
	ds_read_b128 v[86:89], v210 offset:32768
	ds_read_b128 v[90:93], v211 offset:32768
	ds_read_b128 v[94:97], v212 offset:32768
	v_mov_b32_e32 v102, 0
	v_mov_b32_e32 v103, 0
	s_waitcnt lgkmcnt(0)
	v_mfma_f32_32x32x64_f8f6f4 v[66:81], v[82:89], v[146:153], 0
	ds_read_b128 v[82:85], v213 offset:32768
	ds_read_b128 v[86:89], v214 offset:32768
	v_exp_f32_e32 v114, v114
	v_exp_f32_e32 v115, v115
	v_exp_f32_e32 v116, v116
	v_mfma_f32_32x32x64_f8f6f4 v[130:145], v[90:97], v[146:153], 0
	ds_read_b128 v[90:93], v207 offset:32768
	ds_read_b128 v[94:97], v208 offset:32768
	v_exp_f32_e32 v117, v117
	v_exp_f32_e32 v118, v118
	v_exp_f32_e32 v119, v119
	s_waitcnt lgkmcnt(0)
	v_mfma_f32_32x32x64_f8f6f4 v[66:81], v[82:89], v[154:161], v[66:81]
	ds_read_b128 v[82:85], v216
	ds_read_b128 v[86:89], v218
	v_exp_f32_e32 v120, v120
	v_exp_f32_e32 v121, v121
	v_exp_f32_e32 v122, v122
	v_mfma_f32_32x32x64_f8f6f4 v[130:145], v[90:97], v[154:161], v[130:145]
	ds_read_b128 v[90:93], v219
	ds_read_b128 v[94:97], v220
	v_exp_f32_e32 v123, v123
	v_exp_f32_e32 v124, v124
	v_exp_f32_e32 v125, v125
	s_waitcnt lgkmcnt(0)
	v_mfma_f32_32x32x64_f8f6f4 v[66:81], v[82:89], v[162:169], v[66:81]
	v_exp_f32_e32 v126, v126
	v_exp_f32_e32 v127, v127
	v_mfma_f32_32x32x64_f8f6f4 v[130:145], v[90:97], v[162:169], v[130:145]
	ds_read_b64_tr_b8 v[82:83], v200 offset:0
	ds_read_b64_tr_b8 v[84:85], v200 offset:0x800
	ds_read_b64_tr_b8 v[86:87], v200 offset:0x1000
	ds_read_b64_tr_b8 v[88:89], v200 offset:0x1800
	v_cvt_pk_fp8_f32 v102, v98, v99
	v_cvt_pk_fp8_f32 v103, v184, v185
	v_cvt_pk_fp8_f32 v104, v188, v189
	v_cvt_pk_fp8_f32 v105, v110, v111
	v_exp_f32_e32 v128, v128
	v_cvt_pk_fp8_f32 v106, v114, v115
	v_cvt_pk_fp8_f32 v107, v118, v119
	v_exp_f32_e32 v129, v129
	v_cvt_pk_fp8_f32 v108, v122, v123
	v_cvt_pk_fp8_f32 v109, v126, v127
	ds_read_b64_tr_b8 v[90:91], v199 offset:0
	ds_read_b64_tr_b8 v[92:93], v199 offset:0x800
	ds_read_b64_tr_b8 v[94:95], v199 offset:0x1000
	ds_read_b64_tr_b8 v[96:97], v199 offset:0x1800
	v_cvt_pk_fp8_f32 v102, v100, v101 op_sel:[0,0,1]
	v_cvt_pk_fp8_f32 v103, v186, v187 op_sel:[0,0,1]
	v_cvt_pk_fp8_f32 v106, v116, v117 op_sel:[0,0,1]
	v_cvt_pk_fp8_f32 v107, v120, v121 op_sel:[0,0,1]
	v_cvt_pk_fp8_f32 v104, v192, v193 op_sel:[0,0,1]
	v_cvt_pk_fp8_f32 v108, v124, v125 op_sel:[0,0,1]
	v_cvt_pk_fp8_f32 v105, v112, v113 op_sel:[0,0,1]
	v_cvt_pk_fp8_f32 v109, v128, v129 op_sel:[0,0,1]
	s_waitcnt lgkmcnt(4)
	s_mov_b32 m0, s57
	v_mfma_f32_32x32x64_f8f6f4 v[2:17], v[102:109], v[82:89], v[2:17]
	ds_read_b64_tr_b8 v[232:233], v198 offset:0
	ds_read_b64_tr_b8 v[234:235], v198 offset:0x800
	ds_read_b64_tr_b8 v[236:237], v198 offset:0x1000
	ds_read_b64_tr_b8 v[238:239], v198 offset:0x1800
	s_waitcnt lgkmcnt(4)
	s_nop 0
	v_max_f32_e32 v82, v66, v67
	v_max3_f32 v82, v82, v68, v69
	v_max3_f32 v82, v82, v70, v71
	v_max3_f32 v82, v82, v72, v73
	v_max3_f32 v82, v82, v74, v75
	v_max3_f32 v82, v82, v76, v77
	v_max3_f32 v82, v82, v78, v79
	v_max3_f32 v82, v82, v80, v81
	v_max3_f32 v82, v82, v130, v131
	v_max3_f32 v82, v82, v132, v133
	v_max3_f32 v82, v82, v134, v135
	v_max3_f32 v82, v82, v136, v137
	v_max3_f32 v82, v82, v138, v139
	v_max3_f32 v82, v82, v140, v141
	v_max3_f32 v82, v82, v142, v143
	v_max3_f32 v82, v82, v144, v145
	v_mov_b32_e32 v83, v82
	s_nop 1
	v_permlane32_swap_b32_e32 v82, v83
	v_max_f32_e32 v82, v82, v83
	v_sub_f32_e32 v83, v82, v231
	v_cmp_ge_f32_e32 vcc, s46, v83
	s_cmp_eq_u64 vcc, exec
	v_max_f32_e32 v83, v231, v231
	v_max_f32_e32 v241, v83, v82
	s_cselect_b64 vcc, -1, 0
	v_cndmask_b32_e32 v228, v241, v231, vcc
	v_fma_f32 v240, v228, s47, 4.0
	v_mfma_f32_32x32x64_f8f6f4 v[18:33], v[102:109], v[90:97], v[18:33]
	v_pk_add_f32 v[98:99], v[98:99], v[100:101]
	v_pk_fma_f32 v[82:83], v[66:67], s[4:5], v[240:241] op_sel_hi:[1,0,0]
	v_pk_fma_f32 v[66:67], v[130:131], s[4:5], v[240:241] op_sel_hi:[1,0,0]
	ds_read_b64_tr_b8 v[130:131], v197 offset:0
	v_pk_fma_f32 v[84:85], v[68:69], s[4:5], v[240:241] op_sel_hi:[1,0,0]
	v_pk_fma_f32 v[68:69], v[132:133], s[4:5], v[240:241] op_sel_hi:[1,0,0]
	ds_read_b64_tr_b8 v[132:133], v197 offset:0x800
	v_pk_fma_f32 v[86:87], v[70:71], s[4:5], v[240:241] op_sel_hi:[1,0,0]
	v_pk_fma_f32 v[70:71], v[134:135], s[4:5], v[240:241] op_sel_hi:[1,0,0]
	ds_read_b64_tr_b8 v[134:135], v197 offset:0x1000
	v_pk_fma_f32 v[96:97], v[80:81], s[4:5], v[240:241] op_sel_hi:[1,0,0]
	v_pk_fma_f32 v[94:95], v[78:79], s[4:5], v[240:241] op_sel_hi:[1,0,0]
	v_pk_fma_f32 v[92:93], v[76:77], s[4:5], v[240:241] op_sel_hi:[1,0,0]
	v_pk_fma_f32 v[90:91], v[74:75], s[4:5], v[240:241] op_sel_hi:[1,0,0]
	v_pk_fma_f32 v[88:89], v[72:73], s[4:5], v[240:241] op_sel_hi:[1,0,0]
	v_pk_fma_f32 v[80:81], v[144:145], s[4:5], v[240:241] op_sel_hi:[1,0,0]
	v_pk_fma_f32 v[78:79], v[142:143], s[4:5], v[240:241] op_sel_hi:[1,0,0]
	v_pk_fma_f32 v[76:77], v[140:141], s[4:5], v[240:241] op_sel_hi:[1,0,0]
	v_pk_fma_f32 v[74:75], v[138:139], s[4:5], v[240:241] op_sel_hi:[1,0,0]
	v_pk_fma_f32 v[72:73], v[136:137], s[4:5], v[240:241] op_sel_hi:[1,0,0]
	ds_read_b64_tr_b8 v[136:137], v197 offset:0x1800
	s_waitcnt lgkmcnt(4)
	v_pk_add_f32 v[98:99], v[98:99], v[184:185]
	v_mfma_f32_32x32x64_f8f6f4 v[34:49], v[102:109], v[232:239], v[34:49]
	s_waitcnt lgkmcnt(0)
	s_nop 0
	v_exp_f32_e32 v82, v82
	v_exp_f32_e32 v83, v83
	v_exp_f32_e32 v84, v84
	v_exp_f32_e32 v85, v85
	v_mfma_f32_32x32x64_f8f6f4 v[50:65], v[102:109], v[130:137], v[50:65]
	s_barrier
	v_lshl_add_u64 v[102:103], v[190:191], 0, s[18:19]
	global_load_lds_dwordx4 v[102:103], off
	v_pk_add_f32 v[98:99], v[186:187], v[98:99]
	s_nop 0
	v_pk_add_f32 v[98:99], v[188:189], v[98:99]
	s_nop 0
	v_pk_add_f32 v[98:99], v[192:193], v[98:99]
	s_nop 0
	v_pk_add_f32 v[98:99], v[110:111], v[98:99]
	s_nop 0
	v_pk_add_f32 v[98:99], v[112:113], v[98:99]
	s_nop 0
	v_pk_add_f32 v[98:99], v[98:99], v[114:115]
	s_nop 0
	v_pk_add_f32 v[98:99], v[116:117], v[98:99]
	s_nop 0
	v_pk_add_f32 v[98:99], v[118:119], v[98:99]
	s_nop 0
	v_pk_add_f32 v[98:99], v[120:121], v[98:99]
	s_nop 0
	v_pk_add_f32 v[98:99], v[122:123], v[98:99]
	s_nop 0
	v_pk_add_f32 v[98:99], v[124:125], v[98:99]
	s_nop 0
	v_pk_add_f32 v[98:99], v[126:127], v[98:99]
	s_nop 0
	v_pk_add_f32 v[98:99], v[128:129], v[98:99]
	s_nop 0
	v_pk_add_f32 v[98:99], v[98:99], v[98:99] op_sel:[0,1] op_sel_hi:[1,0]
	s_nop 0
	v_sub_f32_e32 v99, v231, v241
	v_mul_f32_e32 v99, 0x3dd53b94, v99
	v_exp_f32_e32 v100, v99
	v_mov_b32_e32 v99, v98
	s_nop 1
	v_permlane32_swap_b32_e32 v98, v99
	v_cndmask_b32_e64 v128, v100, 1.0, vcc
	v_cmp_gt_f32_e32 vcc, 1.0, v128
	s_cbranch_vccz .LBB0_1857
	s_and_saveexec_b64 s[34:35], s[2:3]
	ds_write_b32 v204, v128 offset:128
	s_or_b64 exec, exec, s[34:35]
	s_waitcnt lgkmcnt(0)
	s_nop 15
	s_nop 7
	ds_read2_b32 v[100:101], v201 offset0:32 offset1:33
	ds_read2_b32 v[102:103], v201 offset0:34 offset1:35
	ds_read2_b32 v[104:105], v201 offset0:40 offset1:41
	ds_read2_b32 v[106:107], v201 offset0:42 offset1:43
	s_waitcnt lgkmcnt(0)
	v_pk_mul_f32 v[2:3], v[100:101], v[2:3]
	v_pk_mul_f32 v[18:19], v[100:101], v[18:19]
	v_pk_mul_f32 v[34:35], v[100:101], v[34:35]
	v_pk_mul_f32 v[50:51], v[100:101], v[50:51]
	v_pk_mul_f32 v[4:5], v[4:5], v[102:103]
	v_pk_mul_f32 v[20:21], v[20:21], v[102:103]
	v_pk_mul_f32 v[36:37], v[36:37], v[102:103]
	v_pk_mul_f32 v[52:53], v[52:53], v[102:103]
	v_pk_mul_f32 v[6:7], v[6:7], v[104:105]
	v_pk_mul_f32 v[22:23], v[22:23], v[104:105]
	v_pk_mul_f32 v[38:39], v[38:39], v[104:105]
	v_pk_mul_f32 v[54:55], v[54:55], v[104:105]
	v_pk_mul_f32 v[8:9], v[8:9], v[106:107]
	v_pk_mul_f32 v[24:25], v[24:25], v[106:107]
	v_pk_mul_f32 v[40:41], v[40:41], v[106:107]
	ds_read2_b32 v[100:101], v201 offset0:48 offset1:49
	v_pk_mul_f32 v[56:57], v[56:57], v[106:107]
	ds_read2_b32 v[102:103], v201 offset0:50 offset1:51
	ds_read2_b32 v[104:105], v201 offset0:56 offset1:57
	ds_read2_b32 v[106:107], v201 offset0:58 offset1:59
	s_waitcnt lgkmcnt(0)
	v_pk_mul_f32 v[10:11], v[10:11], v[100:101]
	v_pk_mul_f32 v[26:27], v[26:27], v[100:101]
	v_pk_mul_f32 v[42:43], v[42:43], v[100:101]
	v_pk_mul_f32 v[58:59], v[58:59], v[100:101]
	v_pk_mul_f32 v[12:13], v[12:13], v[102:103]
	v_pk_mul_f32 v[28:29], v[28:29], v[102:103]
	v_pk_mul_f32 v[44:45], v[44:45], v[102:103]
	v_pk_mul_f32 v[60:61], v[60:61], v[102:103]
	v_pk_mul_f32 v[14:15], v[14:15], v[104:105]
	v_pk_mul_f32 v[30:31], v[30:31], v[104:105]
	v_pk_mul_f32 v[46:47], v[46:47], v[104:105]
	v_pk_mul_f32 v[62:63], v[62:63], v[104:105]
	v_pk_mul_f32 v[16:17], v[16:17], v[106:107]
	v_pk_mul_f32 v[32:33], v[32:33], v[106:107]
	v_pk_mul_f32 v[48:49], v[48:49], v[106:107]
	v_pk_mul_f32 v[64:65], v[64:65], v[106:107]

.LBB0_1859:
	ds_read_b128 v[102:105], v209 offset:49152
	ds_read_b128 v[106:109], v210 offset:49152
	ds_read_b128 v[120:123], v211 offset:49152
	ds_read_b128 v[124:127], v212 offset:49152
	v_mov_b32_e32 v118, v171
	v_cvt_pk_fp8_f32 v118, v82, v83
	s_waitcnt lgkmcnt(0)
	v_mfma_f32_32x32x64_f8f6f4 v[86:101], v[102:109], v[146:153], 0
	ds_read_b128 v[130:133], v213 offset:49152
	ds_read_b128 v[134:137], v214 offset:49152
	v_exp_f32_e32 v66, v66
	v_exp_f32_e32 v67, v67
	v_exp_f32_e32 v68, v68
	v_pk_add_f32 v[102:103], v[82:83], v[84:85]
	v_mov_b32_e32 v119, v171
	v_pk_add_f32 v[176:177], v[102:103], v[184:185]
	v_mfma_f32_32x32x64_f8f6f4 v[102:117], v[120:127], v[146:153], 0
	ds_read_b128 v[120:123], v207 offset:49152
	ds_read_b128 v[124:127], v208 offset:49152
	v_exp_f32_e32 v69, v69
	v_exp_f32_e32 v70, v70
	v_exp_f32_e32 v71, v71
	s_waitcnt lgkmcnt(0)
	v_mfma_f32_32x32x64_f8f6f4 v[86:101], v[130:137], v[154:161], v[86:101]
	ds_read_b128 v[130:133], v224
	ds_read_b128 v[134:137], v225
	v_exp_f32_e32 v72, v72
	v_exp_f32_e32 v73, v73
	v_exp_f32_e32 v74, v74
	v_mfma_f32_32x32x64_f8f6f4 v[102:117], v[120:127], v[154:161], v[102:117]
	v_pk_add_f32 v[82:83], v[176:177], v[182:183]
	ds_read_b128 v[146:149], v226
	ds_read_b128 v[150:153], v227
	v_pk_add_f32 v[82:83], v[82:83], v[144:145]
	v_exp_f32_e32 v75, v75
	v_exp_f32_e32 v76, v76
	v_exp_f32_e32 v77, v77
	v_pk_add_f32 v[82:83], v[82:83], v[138:139]
	s_waitcnt lgkmcnt(0)
	v_mfma_f32_32x32x64_f8f6f4 v[86:101], v[130:137], v[162:169], v[86:101]
	v_mov_b32_e32 v122, v171
	v_pk_add_f32 v[82:83], v[82:83], v[142:143]
	v_exp_f32_e32 v78, v78
	v_exp_f32_e32 v79, v79
	v_pk_add_f32 v[82:83], v[82:83], v[140:141]
	v_mfma_f32_32x32x64_f8f6f4 v[102:117], v[146:153], v[162:169], v[102:117]
	v_mov_b32_e32 v123, v171
	v_pk_add_f32 v[82:83], v[82:83], v[66:67]
	v_cvt_pk_fp8_f32 v122, v66, v67
	v_pk_add_f32 v[66:67], v[68:69], v[82:83]
	v_exp_f32_e32 v80, v80
	v_pk_add_f32 v[66:67], v[70:71], v[66:67]
	v_exp_f32_e32 v81, v81
	v_pk_add_f32 v[66:67], v[72:73], v[66:67]
	v_cvt_pk_fp8_f32 v123, v70, v71
	v_pk_add_f32 v[66:67], v[74:75], v[66:67]
	v_mov_b32_e32 v124, v171
	v_pk_add_f32 v[66:67], v[76:77], v[66:67]
	v_cvt_pk_fp8_f32 v122, v68, v69 op_sel:[0,0,1]
	v_pk_add_f32 v[66:67], v[78:79], v[66:67]
	v_cvt_pk_fp8_f32 v124, v74, v75
	v_pk_add_f32 v[66:67], v[80:81], v[66:67]
	v_mov_b32_e32 v125, v171
	v_pk_add_f32 v[126:127], v[66:67], v[66:67] op_sel:[0,1] op_sel_hi:[1,0]
	ds_read_b64_tr_b8 v[66:67], v206 offset:0
	ds_read_b64_tr_b8 v[68:69], v206 offset:0x800
	ds_read_b64_tr_b8 v[70:71], v206 offset:0x1000
	v_cvt_pk_fp8_f32 v123, v72, v73 op_sel:[0,0,1]
	v_mov_b32_e32 v120, v171
	v_mov_b32_e32 v121, v171
	v_cvt_pk_fp8_f32 v125, v78, v79
	ds_read_b64_tr_b8 v[72:73], v206 offset:0x1800
	v_cvt_pk_fp8_f32 v119, v184, v185
	v_cvt_pk_fp8_f32 v120, v144, v145
	v_cvt_pk_fp8_f32 v121, v142, v143
	ds_read_b64_tr_b8 v[74:75], v205 offset:0
	v_cvt_pk_fp8_f32 v124, v76, v77 op_sel:[0,0,1]
	ds_read_b64_tr_b8 v[76:77], v205 offset:0x800
	ds_read_b64_tr_b8 v[78:79], v205 offset:0x1000
	v_cvt_pk_fp8_f32 v125, v80, v81 op_sel:[0,0,1]
	ds_read_b64_tr_b8 v[80:81], v205 offset:0x1800
	v_cvt_pk_fp8_f32 v118, v84, v85 op_sel:[0,0,1]
	v_cvt_pk_fp8_f32 v119, v182, v183 op_sel:[0,0,1]
	v_cvt_pk_fp8_f32 v120, v138, v139 op_sel:[0,0,1]
	v_cvt_pk_fp8_f32 v121, v140, v141 op_sel:[0,0,1]
	s_waitcnt lgkmcnt(4)
	v_mov_b32_e32 v127, v126
	v_mfma_f32_32x32x64_f8f6f4 v[2:17], v[118:125], v[66:73], v[2:17]
	ds_read_b64_tr_b8 v[130:131], v203 offset:0
	ds_read_b64_tr_b8 v[132:133], v203 offset:0x800
	ds_read_b64_tr_b8 v[134:135], v203 offset:0x1000
	ds_read_b64_tr_b8 v[136:137], v203 offset:0x1800
	s_waitcnt lgkmcnt(4)
	s_nop 0
	v_max_f32_e32 v66, v86, v87
	v_max3_f32 v66, v66, v88, v89
	v_max3_f32 v66, v66, v90, v91
	v_max3_f32 v66, v66, v92, v93
	v_max3_f32 v66, v66, v94, v95
	v_max3_f32 v66, v66, v96, v97
	v_max3_f32 v66, v66, v98, v99
	v_max3_f32 v66, v66, v100, v101
	v_max3_f32 v66, v66, v102, v103
	v_max3_f32 v66, v66, v104, v105
	v_max3_f32 v66, v66, v106, v107
	v_max3_f32 v66, v66, v108, v109
	v_max3_f32 v66, v66, v110, v111
	v_max3_f32 v66, v66, v112, v113
	v_max3_f32 v66, v66, v114, v115
	v_max3_f32 v66, v66, v116, v117
	v_mov_b32_e32 v67, v66
	s_nop 1
	v_permlane32_swap_b32_e32 v66, v67
	v_max_f32_e32 v66, v66, v67
	v_sub_f32_e32 v67, v66, v228
	v_cmp_ge_f32_e32 vcc, s46, v67
	s_cmp_eq_u64 vcc, exec
	v_max_f32_e32 v66, v228, v66
	s_cselect_b64 vcc, -1, 0
	v_sub_f32_e32 v67, v228, v66
	v_cndmask_b32_e32 v66, v66, v228, vcc
	v_mul_f32_e32 v83, 0x3dd53b94, v67
	v_fma_f32 v82, v66, s47, 4.0
	v_mfma_f32_32x32x64_f8f6f4 v[18:33], v[118:125], v[74:81], v[18:33]
	v_permlane32_swap_b32_e32 v126, v127
	v_pk_fma_f32 v[80:81], v[100:101], s[4:5], v[82:83] op_sel_hi:[1,0,0]
	ds_read_b64_tr_b8 v[100:101], v202 offset:0
	v_pk_fma_f32 v[78:79], v[98:99], s[4:5], v[82:83] op_sel_hi:[1,0,0]
	v_pk_fma_f32 v[76:77], v[96:97], s[4:5], v[82:83] op_sel_hi:[1,0,0]
	v_pk_fma_f32 v[74:75], v[94:95], s[4:5], v[82:83] op_sel_hi:[1,0,0]
	v_pk_fma_f32 v[72:73], v[92:93], s[4:5], v[82:83] op_sel_hi:[1,0,0]
	v_pk_fma_f32 v[70:71], v[90:91], s[4:5], v[82:83] op_sel_hi:[1,0,0]
	v_pk_fma_f32 v[68:69], v[88:89], s[4:5], v[82:83] op_sel_hi:[1,0,0]
	v_pk_fma_f32 v[66:67], v[86:87], s[4:5], v[82:83] op_sel_hi:[1,0,0]
	v_exp_f32_e32 v98, v83
	v_pk_fma_f32 v[96:97], v[116:117], s[4:5], v[82:83] op_sel_hi:[1,0,0]
	v_pk_fma_f32 v[94:95], v[114:115], s[4:5], v[82:83] op_sel_hi:[1,0,0]
	v_pk_fma_f32 v[92:93], v[112:113], s[4:5], v[82:83] op_sel_hi:[1,0,0]
	v_pk_fma_f32 v[90:91], v[110:111], s[4:5], v[82:83] op_sel_hi:[1,0,0]
	v_pk_fma_f32 v[88:89], v[108:109], s[4:5], v[82:83] op_sel_hi:[1,0,0]
	v_pk_fma_f32 v[86:87], v[106:107], s[4:5], v[82:83] op_sel_hi:[1,0,0]
	v_pk_fma_f32 v[84:85], v[104:105], s[4:5], v[82:83] op_sel_hi:[1,0,0]
	v_pk_fma_f32 v[82:83], v[102:103], s[4:5], v[82:83] op_sel_hi:[1,0,0]
	ds_read_b64_tr_b8 v[102:103], v202 offset:0x800
	ds_read_b64_tr_b8 v[104:105], v202 offset:0x1000
	ds_read_b64_tr_b8 v[106:107], v202 offset:0x1800
	s_waitcnt lgkmcnt(4)
	v_cndmask_b32_e64 v98, v98, 1.0, vcc
	v_mfma_f32_32x32x64_f8f6f4 v[34:49], v[118:125], v[130:137], v[34:49]
	s_waitcnt lgkmcnt(0)
	v_cmp_gt_f32_e32 vcc, 1.0, v98
	v_exp_f32_e32 v66, v66
	v_exp_f32_e32 v67, v67
	v_exp_f32_e32 v68, v68
	v_exp_f32_e32 v69, v69
	v_mfma_f32_32x32x64_f8f6f4 v[50:65], v[118:125], v[100:107], v[50:65]
	s_cbranch_vccz .LBB0_1863
	s_and_saveexec_b64 s[34:35], s[2:3]
	ds_write_b32 v204, v98 offset:128
	s_or_b64 exec, exec, s[34:35]
	s_waitcnt lgkmcnt(0)
	s_nop 15
	s_nop 7
	ds_read2_b32 v[100:101], v201 offset0:32 offset1:33
	ds_read2_b32 v[102:103], v201 offset0:34 offset1:35
	ds_read2_b32 v[104:105], v201 offset0:40 offset1:41
	ds_read2_b32 v[106:107], v201 offset0:42 offset1:43
	s_waitcnt lgkmcnt(0)
	v_pk_mul_f32 v[2:3], v[100:101], v[2:3]
	v_pk_mul_f32 v[18:19], v[100:101], v[18:19]
	v_pk_mul_f32 v[34:35], v[100:101], v[34:35]
	v_pk_mul_f32 v[50:51], v[100:101], v[50:51]
	v_pk_mul_f32 v[4:5], v[4:5], v[102:103]
	v_pk_mul_f32 v[20:21], v[20:21], v[102:103]
	v_pk_mul_f32 v[36:37], v[36:37], v[102:103]
	v_pk_mul_f32 v[52:53], v[52:53], v[102:103]
	v_pk_mul_f32 v[6:7], v[6:7], v[104:105]
	v_pk_mul_f32 v[22:23], v[22:23], v[104:105]
	v_pk_mul_f32 v[38:39], v[38:39], v[104:105]
	v_pk_mul_f32 v[54:55], v[54:55], v[104:105]
	v_pk_mul_f32 v[8:9], v[8:9], v[106:107]
	v_pk_mul_f32 v[24:25], v[24:25], v[106:107]
	v_pk_mul_f32 v[40:41], v[40:41], v[106:107]
	ds_read2_b32 v[100:101], v201 offset0:48 offset1:49
	v_pk_mul_f32 v[56:57], v[56:57], v[106:107]
	ds_read2_b32 v[102:103], v201 offset0:50 offset1:51
	ds_read2_b32 v[104:105], v201 offset0:56 offset1:57
	ds_read2_b32 v[106:107], v201 offset0:58 offset1:59
	s_waitcnt lgkmcnt(0)
	v_pk_mul_f32 v[10:11], v[10:11], v[100:101]
	v_pk_mul_f32 v[26:27], v[26:27], v[100:101]
	v_pk_mul_f32 v[42:43], v[42:43], v[100:101]
	v_pk_mul_f32 v[58:59], v[58:59], v[100:101]
	v_pk_mul_f32 v[12:13], v[12:13], v[102:103]
	v_pk_mul_f32 v[28:29], v[28:29], v[102:103]
	v_pk_mul_f32 v[44:45], v[44:45], v[102:103]
	v_pk_mul_f32 v[60:61], v[60:61], v[102:103]
	v_pk_mul_f32 v[14:15], v[14:15], v[104:105]
	v_pk_mul_f32 v[30:31], v[30:31], v[104:105]
	v_pk_mul_f32 v[46:47], v[46:47], v[104:105]
	v_pk_mul_f32 v[62:63], v[62:63], v[104:105]
	v_pk_mul_f32 v[16:17], v[16:17], v[106:107]
	v_pk_mul_f32 v[32:33], v[32:33], v[106:107]
	v_pk_mul_f32 v[48:49], v[48:49], v[106:107]
	v_pk_mul_f32 v[64:65], v[64:65], v[106:107]

.LBB0_1883:
	v_lshl_add_u64 v[138:139], v[166:167], 0, s[4:5]
	s_add_i32 s46, s31, 0x8000
	v_lshl_add_u64 v[86:87], v[138:139], 0, s[8:9]
	s_mov_b32 m0, s46
	s_nop 0
	global_load_lds_dwordx4 v[86:87], off
	ds_read_b128 v[106:109], v198 offset:49152
	ds_read_b128 v[102:105], v197 offset:49152
	ds_read_b128 v[130:133], v197 offset:53248
	ds_read_b128 v[134:137], v198 offset:53248
	s_mov_b32 m0, s31
	s_waitcnt lgkmcnt(0)
	v_mfma_f32_32x32x64_f8f6f4 v[86:101], v[102:109], v[154:161], 0
	s_nop 0
	v_exp_f32_e32 v66, v66
	v_exp_f32_e32 v67, v67
	v_exp_f32_e32 v68, v68
	v_exp_f32_e32 v69, v69
	ds_read_b128 v[102:105], v195 offset:49152
	ds_read_b128 v[106:109], v196 offset:49152
	v_mfma_f32_32x32x64_f8f6f4 v[114:129], v[130:137], v[154:161], 0
	ds_read_b128 v[202:205], v195 offset:53248
	ds_read_b128 v[206:209], v196 offset:53248
	v_exp_f32_e32 v70, v70
	v_exp_f32_e32 v71, v71
	v_exp_f32_e32 v72, v72
	v_exp_f32_e32 v73, v73
	s_waitcnt lgkmcnt(0)
	v_mfma_f32_32x32x64_f8f6f4 v[86:101], v[102:109], v[146:153], v[86:101]
	v_exp_f32_e32 v74, v74
	v_exp_f32_e32 v75, v75
	v_exp_f32_e32 v76, v76
	v_exp_f32_e32 v77, v77
	v_mfma_f32_32x32x64_f8f6f4 v[114:129], v[202:209], v[146:153], v[114:129]
	ds_read_b64_tr_b8 v[102:103], v194 offset:0
	ds_read_b64_tr_b8 v[104:105], v194 offset:0x800
	ds_read_b64_tr_b8 v[106:107], v194 offset:0x1000
	v_exp_f32_e32 v78, v78
	v_exp_f32_e32 v79, v79
	ds_read_b64_tr_b8 v[108:109], v194 offset:0x1800
	v_cvt_pk_fp8_f32 v130, v82, v83
	v_exp_f32_e32 v80, v80
	v_exp_f32_e32 v81, v81
	v_cvt_pk_fp8_f32 v134, v66, v67
	v_cvt_pk_fp8_f32 v131, v172, v173
	v_cvt_pk_fp8_f32 v135, v70, v71
	v_cvt_pk_fp8_f32 v132, v168, v169
	v_cvt_pk_fp8_f32 v136, v74, v75
	v_cvt_pk_fp8_f32 v133, v144, v145
	v_cvt_pk_fp8_f32 v137, v78, v79
	ds_read_b64_tr_b8 v[204:205], v193 offset:0
	ds_read_b64_tr_b8 v[206:207], v193 offset:0x800
	ds_read_b64_tr_b8 v[208:209], v193 offset:0x1000
	ds_read_b64_tr_b8 v[210:211], v193 offset:0x1800
	v_cvt_pk_fp8_f32 v130, v84, v85 op_sel:[0,0,1]
	v_cvt_pk_fp8_f32 v134, v68, v69 op_sel:[0,0,1]
	v_cvt_pk_fp8_f32 v131, v170, v171 op_sel:[0,0,1]
	v_cvt_pk_fp8_f32 v135, v72, v73 op_sel:[0,0,1]
	v_cvt_pk_fp8_f32 v132, v140, v141 op_sel:[0,0,1]
	v_cvt_pk_fp8_f32 v136, v76, v77 op_sel:[0,0,1]
	v_cvt_pk_fp8_f32 v133, v142, v143 op_sel:[0,0,1]
	v_cvt_pk_fp8_f32 v137, v80, v81 op_sel:[0,0,1]
	s_waitcnt lgkmcnt(4)
	v_pk_add_f32 v[82:83], v[82:83], v[84:85]
	v_mfma_f32_32x32x64_f8f6f4 v[2:17], v[130:137], v[102:109], v[2:17]
	ds_read_b64_tr_b8 v[212:213], v192 offset:0
	ds_read_b64_tr_b8 v[214:215], v192 offset:0x800
	ds_read_b64_tr_b8 v[216:217], v192 offset:0x1000
	ds_read_b64_tr_b8 v[218:219], v192 offset:0x1800
	s_waitcnt lgkmcnt(4)
	s_nop 0
	v_max_f32_e32 v102, v86, v87
	v_max3_f32 v102, v102, v88, v89
	v_max3_f32 v102, v102, v90, v91
	v_max3_f32 v102, v102, v92, v93
	v_max3_f32 v102, v102, v94, v95
	v_max3_f32 v102, v102, v96, v97
	v_max3_f32 v102, v102, v98, v99
	v_max3_f32 v102, v102, v100, v101
	v_max3_f32 v102, v102, v114, v115
	v_max3_f32 v102, v102, v116, v117
	v_max3_f32 v102, v102, v118, v119
	v_max3_f32 v102, v102, v120, v121
	v_max3_f32 v102, v102, v122, v123
	v_max3_f32 v102, v102, v124, v125
	v_max3_f32 v102, v102, v126, v127
	v_max3_f32 v102, v102, v128, v129
	v_mov_b32_e32 v103, v102
	s_nop 1
	v_permlane32_swap_b32_e32 v102, v103
	v_max_f32_e32 v102, v102, v103
	v_sub_f32_e32 v103, v102, v200
	v_cmp_ge_f32_e32 vcc, s38, v103
	s_cmp_eq_u64 vcc, exec
	v_max_f32_e32 v103, v200, v200
	v_max_f32_e32 v176, v103, v102
	s_cselect_b64 vcc, -1, 0
	v_cndmask_b32_e32 v202, v176, v200, vcc
	v_fma_f32 v174, v202, s39, 4.0
	v_mfma_f32_32x32x64_f8f6f4 v[18:33], v[130:137], v[204:211], v[18:33]
	v_pk_add_f32 v[82:83], v[172:173], v[82:83]
	v_pk_fma_f32 v[110:111], v[98:99], s[6:7], v[174:175] op_sel_hi:[1,0,0]
	v_pk_fma_f32 v[98:99], v[86:87], s[6:7], v[174:175] op_sel_hi:[1,0,0]
	ds_read_b64_tr_b8 v[86:87], v190 offset:0
	v_pk_fma_f32 v[112:113], v[100:101], s[6:7], v[174:175] op_sel_hi:[1,0,0]
	v_pk_fma_f32 v[100:101], v[88:89], s[6:7], v[174:175] op_sel_hi:[1,0,0]
	ds_read_b64_tr_b8 v[88:89], v190 offset:0x800
	v_pk_fma_f32 v[102:103], v[90:91], s[6:7], v[174:175] op_sel_hi:[1,0,0]
	ds_read_b64_tr_b8 v[90:91], v190 offset:0x1000
	v_pk_fma_f32 v[108:109], v[96:97], s[6:7], v[174:175] op_sel_hi:[1,0,0]
	v_pk_fma_f32 v[106:107], v[94:95], s[6:7], v[174:175] op_sel_hi:[1,0,0]
	v_pk_fma_f32 v[104:105], v[92:93], s[6:7], v[174:175] op_sel_hi:[1,0,0]
	v_pk_fma_f32 v[128:129], v[128:129], s[6:7], v[174:175] op_sel_hi:[1,0,0]
	v_pk_fma_f32 v[126:127], v[126:127], s[6:7], v[174:175] op_sel_hi:[1,0,0]
	v_pk_fma_f32 v[124:125], v[124:125], s[6:7], v[174:175] op_sel_hi:[1,0,0]
	v_pk_fma_f32 v[122:123], v[122:123], s[6:7], v[174:175] op_sel_hi:[1,0,0]
	v_pk_fma_f32 v[120:121], v[120:121], s[6:7], v[174:175] op_sel_hi:[1,0,0]
	v_pk_fma_f32 v[118:119], v[118:119], s[6:7], v[174:175] op_sel_hi:[1,0,0]
	v_pk_fma_f32 v[116:117], v[116:117], s[6:7], v[174:175] op_sel_hi:[1,0,0]
	v_pk_fma_f32 v[114:115], v[114:115], s[6:7], v[174:175] op_sel_hi:[1,0,0]
	ds_read_b64_tr_b8 v[92:93], v190 offset:0x1800
	s_waitcnt lgkmcnt(4)
	v_lshl_add_u64 v[174:175], v[164:165], 0, s[4:5]
	v_mfma_f32_32x32x64_f8f6f4 v[34:49], v[130:137], v[212:219], v[34:49]
	s_waitcnt lgkmcnt(0)
	v_pk_add_f32 v[82:83], v[170:171], v[82:83]
	v_exp_f32_e32 v98, v98
	v_exp_f32_e32 v99, v99
	v_exp_f32_e32 v100, v100
	v_exp_f32_e32 v101, v101
	v_mfma_f32_32x32x64_f8f6f4 v[50:65], v[130:137], v[86:93], v[50:65]
	s_barrier
	v_lshl_add_u64 v[86:87], v[174:175], 0, s[10:11]
	global_load_lds_dwordx4 v[86:87], off
	v_pk_add_f32 v[82:83], v[168:169], v[82:83]
	s_nop 0
	v_pk_add_f32 v[82:83], v[140:141], v[82:83]
	s_nop 0
	v_pk_add_f32 v[82:83], v[144:145], v[82:83]
	s_nop 0
	v_pk_add_f32 v[82:83], v[142:143], v[82:83]
	s_nop 0
	v_pk_add_f32 v[66:67], v[82:83], v[66:67]
	s_nop 0
	v_pk_add_f32 v[66:67], v[68:69], v[66:67]
	s_nop 0
	v_pk_add_f32 v[66:67], v[70:71], v[66:67]
	s_nop 0
	v_pk_add_f32 v[66:67], v[72:73], v[66:67]
	s_nop 0
	v_pk_add_f32 v[66:67], v[74:75], v[66:67]
	s_nop 0
	v_pk_add_f32 v[66:67], v[76:77], v[66:67]
	s_nop 0
	v_pk_add_f32 v[66:67], v[78:79], v[66:67]
	s_nop 0
	v_pk_add_f32 v[66:67], v[80:81], v[66:67]
	s_nop 0
	v_pk_add_f32 v[168:169], v[66:67], v[66:67] op_sel:[0,1] op_sel_hi:[1,0]
	v_sub_f32_e32 v66, v200, v176
	v_mul_f32_e32 v66, 0x3e0293ee, v66
	v_exp_f32_e32 v66, v66
	v_mov_b32_e32 v201, v168
	s_nop 1
	v_permlane32_swap_b32_e32 v168, v201
	v_cndmask_b32_e64 v169, v66, 1.0, vcc
	v_cmp_gt_f32_e32 vcc, 1.0, v169
	s_cbranch_vccz .LBB0_1887
	s_and_saveexec_b64 s[28:29], s[2:3]
	ds_write_b32 v191, v169 offset:128
	s_or_b64 exec, exec, s[28:29]
	s_waitcnt lgkmcnt(0)
	s_nop 15
	s_nop 7
	ds_read2_b32 v[66:67], v189 offset0:32 offset1:33
	ds_read2_b32 v[68:69], v189 offset0:34 offset1:35
	ds_read2_b32 v[70:71], v189 offset0:40 offset1:41
	ds_read2_b32 v[72:73], v189 offset0:42 offset1:43
	s_waitcnt lgkmcnt(0)
	v_pk_mul_f32 v[2:3], v[66:67], v[2:3]
	v_pk_mul_f32 v[18:19], v[66:67], v[18:19]
	v_pk_mul_f32 v[34:35], v[66:67], v[34:35]
	v_pk_mul_f32 v[50:51], v[66:67], v[50:51]
	v_pk_mul_f32 v[4:5], v[4:5], v[68:69]
	v_pk_mul_f32 v[20:21], v[20:21], v[68:69]
	v_pk_mul_f32 v[36:37], v[36:37], v[68:69]
	v_pk_mul_f32 v[52:53], v[52:53], v[68:69]
	v_pk_mul_f32 v[6:7], v[6:7], v[70:71]
	v_pk_mul_f32 v[22:23], v[22:23], v[70:71]
	v_pk_mul_f32 v[38:39], v[38:39], v[70:71]
	v_pk_mul_f32 v[54:55], v[54:55], v[70:71]
	v_pk_mul_f32 v[8:9], v[8:9], v[72:73]
	v_pk_mul_f32 v[24:25], v[24:25], v[72:73]
	v_pk_mul_f32 v[40:41], v[40:41], v[72:73]
	ds_read2_b32 v[66:67], v189 offset0:48 offset1:49
	v_pk_mul_f32 v[56:57], v[56:57], v[72:73]
	ds_read2_b32 v[68:69], v189 offset0:50 offset1:51
	ds_read2_b32 v[70:71], v189 offset0:56 offset1:57
	ds_read2_b32 v[72:73], v189 offset0:58 offset1:59
	s_waitcnt lgkmcnt(0)
	v_pk_mul_f32 v[10:11], v[10:11], v[66:67]
	v_pk_mul_f32 v[26:27], v[26:27], v[66:67]
	v_pk_mul_f32 v[42:43], v[42:43], v[66:67]
	v_pk_mul_f32 v[58:59], v[58:59], v[66:67]
	v_pk_mul_f32 v[12:13], v[12:13], v[68:69]
	v_pk_mul_f32 v[28:29], v[28:29], v[68:69]
	v_pk_mul_f32 v[44:45], v[44:45], v[68:69]
	v_pk_mul_f32 v[60:61], v[60:61], v[68:69]
	v_pk_mul_f32 v[14:15], v[14:15], v[70:71]
	v_pk_mul_f32 v[30:31], v[30:31], v[70:71]
	v_pk_mul_f32 v[46:47], v[46:47], v[70:71]
	v_pk_mul_f32 v[62:63], v[62:63], v[70:71]
	v_pk_mul_f32 v[16:17], v[16:17], v[72:73]
	v_pk_mul_f32 v[32:33], v[32:33], v[72:73]
	v_pk_mul_f32 v[48:49], v[48:49], v[72:73]
	v_pk_mul_f32 v[64:65], v[64:65], v[72:73]
.LBB0_1887:
	s_waitcnt vmcnt(1)
	s_add_i32 s49, s31, 0xc000
	s_barrier
	v_lshl_add_u64 v[66:67], v[138:139], 0, s[12:13]
	s_mov_b32 m0, s49
	v_exp_f32_e32 v170, v102
	global_load_lds_dwordx4 v[66:67], off
	v_exp_f32_e32 v171, v103
	v_exp_f32_e32 v172, v104
	v_exp_f32_e32 v173, v105
	v_exp_f32_e32 v176, v106
	v_exp_f32_e32 v177, v107
	v_exp_f32_e32 v178, v108
	v_exp_f32_e32 v179, v109
	v_exp_f32_e32 v110, v110
	v_exp_f32_e32 v111, v111
	v_exp_f32_e32 v112, v112
	v_exp_f32_e32 v113, v113
	ds_read_b128 v[86:89], v198 offset:32768
	ds_read_b128 v[82:85], v197 offset:32768
	ds_read_b128 v[90:93], v197 offset:36864
	ds_read_b128 v[94:97], v198 offset:36864
	s_waitcnt lgkmcnt(0)
	v_mfma_f32_32x32x64_f8f6f4 v[66:81], v[82:89], v[154:161], 0
	ds_read_b128 v[82:85], v195 offset:32768
	ds_read_b128 v[86:89], v196 offset:32768
	v_exp_f32_e32 v114, v114
	v_exp_f32_e32 v115, v115
	v_exp_f32_e32 v116, v116
	v_exp_f32_e32 v117, v117
	v_mfma_f32_32x32x64_f8f6f4 v[130:145], v[90:97], v[154:161], 0
	ds_read_b128 v[90:93], v195 offset:36864
	ds_read_b128 v[94:97], v196 offset:36864
	v_exp_f32_e32 v118, v118
	v_exp_f32_e32 v119, v119
	v_exp_f32_e32 v120, v120
	v_exp_f32_e32 v121, v121
	s_waitcnt lgkmcnt(0)
	v_mfma_f32_32x32x64_f8f6f4 v[66:81], v[82:89], v[146:153], v[66:81]
	v_exp_f32_e32 v122, v122
	v_exp_f32_e32 v123, v123
	v_exp_f32_e32 v124, v124
	v_exp_f32_e32 v125, v125
	v_mfma_f32_32x32x64_f8f6f4 v[130:145], v[90:97], v[146:153], v[130:145]
	ds_read_b64_tr_b8 v[82:83], v188 offset:0
	ds_read_b64_tr_b8 v[84:85], v188 offset:0x800
	ds_read_b64_tr_b8 v[86:87], v188 offset:0x1000
	v_exp_f32_e32 v126, v126
	v_exp_f32_e32 v127, v127
	ds_read_b64_tr_b8 v[88:89], v188 offset:0x1800
	v_cvt_pk_fp8_f32 v102, v98, v99
	v_exp_f32_e32 v128, v128
	v_exp_f32_e32 v129, v129
	v_cvt_pk_fp8_f32 v106, v114, v115
	v_cvt_pk_fp8_f32 v103, v170, v171
	v_cvt_pk_fp8_f32 v107, v118, v119
	v_cvt_pk_fp8_f32 v104, v176, v177
	v_cvt_pk_fp8_f32 v108, v122, v123
	v_cvt_pk_fp8_f32 v105, v110, v111
	v_cvt_pk_fp8_f32 v109, v126, v127
	ds_read_b64_tr_b8 v[90:91], v187 offset:0
	ds_read_b64_tr_b8 v[92:93], v187 offset:0x800
	ds_read_b64_tr_b8 v[94:95], v187 offset:0x1000
	ds_read_b64_tr_b8 v[96:97], v187 offset:0x1800
	v_cvt_pk_fp8_f32 v102, v100, v101 op_sel:[0,0,1]
	v_cvt_pk_fp8_f32 v106, v116, v117 op_sel:[0,0,1]
	v_cvt_pk_fp8_f32 v103, v172, v173 op_sel:[0,0,1]
	v_cvt_pk_fp8_f32 v107, v120, v121 op_sel:[0,0,1]
	v_cvt_pk_fp8_f32 v104, v178, v179 op_sel:[0,0,1]
	v_cvt_pk_fp8_f32 v108, v124, v125 op_sel:[0,0,1]
	v_cvt_pk_fp8_f32 v105, v112, v113 op_sel:[0,0,1]
	v_cvt_pk_fp8_f32 v109, v128, v129 op_sel:[0,0,1]
	s_waitcnt lgkmcnt(4)
	s_mov_b32 m0, s47
	v_mfma_f32_32x32x64_f8f6f4 v[2:17], v[102:109], v[82:89], v[2:17]
	ds_read_b64_tr_b8 v[204:205], v186 offset:0
	ds_read_b64_tr_b8 v[206:207], v186 offset:0x800
	ds_read_b64_tr_b8 v[208:209], v186 offset:0x1000
	ds_read_b64_tr_b8 v[210:211], v186 offset:0x1800
	s_waitcnt lgkmcnt(4)
	s_nop 0
	v_max_f32_e32 v82, v66, v67
	v_max3_f32 v82, v82, v68, v69
	v_max3_f32 v82, v82, v70, v71
	v_max3_f32 v82, v82, v72, v73
	v_max3_f32 v82, v82, v74, v75
	v_max3_f32 v82, v82, v76, v77
	v_max3_f32 v82, v82, v78, v79
	v_max3_f32 v82, v82, v80, v81
	v_max3_f32 v82, v82, v130, v131
	v_max3_f32 v82, v82, v132, v133
	v_max3_f32 v82, v82, v134, v135
	v_max3_f32 v82, v82, v136, v137
	v_max3_f32 v82, v82, v138, v139
	v_max3_f32 v82, v82, v140, v141
	v_max3_f32 v82, v82, v142, v143
	v_max3_f32 v82, v82, v144, v145
	v_mov_b32_e32 v83, v82
	s_nop 1
	v_permlane32_swap_b32_e32 v82, v83
	v_max_f32_e32 v82, v82, v83
	v_sub_f32_e32 v83, v82, v202
	v_cmp_ge_f32_e32 vcc, s38, v83
	s_cmp_eq_u64 vcc, exec
	v_max_f32_e32 v83, v202, v202
	v_max_f32_e32 v203, v83, v82
	s_cselect_b64 vcc, -1, 0
	v_cndmask_b32_e32 v200, v203, v202, vcc
	v_fma_f32 v212, v200, s39, 4.0
	v_mfma_f32_32x32x64_f8f6f4 v[18:33], v[102:109], v[90:97], v[18:33]
	v_pk_add_f32 v[98:99], v[98:99], v[100:101]
	v_pk_fma_f32 v[82:83], v[66:67], s[6:7], v[212:213] op_sel_hi:[1,0,0]
	v_pk_fma_f32 v[66:67], v[130:131], s[6:7], v[212:213] op_sel_hi:[1,0,0]
	ds_read_b64_tr_b8 v[130:131], v185 offset:0
	v_pk_fma_f32 v[84:85], v[68:69], s[6:7], v[212:213] op_sel_hi:[1,0,0]
	v_pk_fma_f32 v[68:69], v[132:133], s[6:7], v[212:213] op_sel_hi:[1,0,0]
	ds_read_b64_tr_b8 v[132:133], v185 offset:0x800
	v_pk_fma_f32 v[86:87], v[70:71], s[6:7], v[212:213] op_sel_hi:[1,0,0]
	v_pk_fma_f32 v[70:71], v[134:135], s[6:7], v[212:213] op_sel_hi:[1,0,0]
	ds_read_b64_tr_b8 v[134:135], v185 offset:0x1000
	v_pk_fma_f32 v[96:97], v[80:81], s[6:7], v[212:213] op_sel_hi:[1,0,0]
	v_pk_fma_f32 v[94:95], v[78:79], s[6:7], v[212:213] op_sel_hi:[1,0,0]
	v_pk_fma_f32 v[92:93], v[76:77], s[6:7], v[212:213] op_sel_hi:[1,0,0]
	v_pk_fma_f32 v[90:91], v[74:75], s[6:7], v[212:213] op_sel_hi:[1,0,0]
	v_pk_fma_f32 v[88:89], v[72:73], s[6:7], v[212:213] op_sel_hi:[1,0,0]
	v_pk_fma_f32 v[80:81], v[144:145], s[6:7], v[212:213] op_sel_hi:[1,0,0]
	v_pk_fma_f32 v[78:79], v[142:143], s[6:7], v[212:213] op_sel_hi:[1,0,0]
	v_pk_fma_f32 v[76:77], v[140:141], s[6:7], v[212:213] op_sel_hi:[1,0,0]
	v_pk_fma_f32 v[74:75], v[138:139], s[6:7], v[212:213] op_sel_hi:[1,0,0]
	v_pk_fma_f32 v[72:73], v[136:137], s[6:7], v[212:213] op_sel_hi:[1,0,0]
	ds_read_b64_tr_b8 v[136:137], v185 offset:0x1800
	s_waitcnt lgkmcnt(4)
	v_pk_add_f32 v[98:99], v[98:99], v[170:171]
	v_mfma_f32_32x32x64_f8f6f4 v[34:49], v[102:109], v[204:211], v[34:49]
	s_waitcnt lgkmcnt(0)
	s_nop 0
	v_exp_f32_e32 v82, v82
	v_exp_f32_e32 v83, v83
	v_exp_f32_e32 v84, v84
	v_exp_f32_e32 v85, v85
	v_mfma_f32_32x32x64_f8f6f4 v[50:65], v[102:109], v[130:137], v[50:65]
	s_barrier
	v_lshl_add_u64 v[102:103], v[174:175], 0, s[14:15]
	global_load_lds_dwordx4 v[102:103], off
	v_pk_add_f32 v[98:99], v[172:173], v[98:99]
	s_nop 0
	v_pk_add_f32 v[98:99], v[176:177], v[98:99]
	s_nop 0
	v_pk_add_f32 v[98:99], v[178:179], v[98:99]
	s_nop 0
	v_pk_add_f32 v[98:99], v[110:111], v[98:99]
	s_nop 0
	v_pk_add_f32 v[98:99], v[112:113], v[98:99]
	s_nop 0
	v_pk_add_f32 v[98:99], v[98:99], v[114:115]
	s_nop 0
	v_pk_add_f32 v[98:99], v[116:117], v[98:99]
	s_nop 0
	v_pk_add_f32 v[98:99], v[118:119], v[98:99]
	s_nop 0
	v_pk_add_f32 v[98:99], v[120:121], v[98:99]
	s_nop 0
	v_pk_add_f32 v[98:99], v[122:123], v[98:99]
	s_nop 0
	v_pk_add_f32 v[98:99], v[124:125], v[98:99]
	s_nop 0
	v_pk_add_f32 v[98:99], v[126:127], v[98:99]
	s_nop 0
	v_pk_add_f32 v[98:99], v[128:129], v[98:99]
	s_nop 0
	v_pk_add_f32 v[98:99], v[98:99], v[98:99] op_sel:[0,1] op_sel_hi:[1,0]
	s_nop 0
	v_sub_f32_e32 v99, v202, v203
	v_mul_f32_e32 v99, 0x3e0293ee, v99
	v_exp_f32_e32 v100, v99
	v_mov_b32_e32 v99, v98
	s_nop 1
	v_permlane32_swap_b32_e32 v98, v99
	v_cndmask_b32_e64 v174, v100, 1.0, vcc
	v_cmp_gt_f32_e32 vcc, 1.0, v174
	s_cbranch_vccz .LBB0_1891
	s_and_saveexec_b64 s[28:29], s[2:3]
	ds_write_b32 v191, v174 offset:128
	s_or_b64 exec, exec, s[28:29]
	s_waitcnt lgkmcnt(0)
	s_nop 15
	s_nop 7
	ds_read2_b32 v[100:101], v189 offset0:32 offset1:33
	ds_read2_b32 v[102:103], v189 offset0:34 offset1:35
	ds_read2_b32 v[104:105], v189 offset0:40 offset1:41
	ds_read2_b32 v[106:107], v189 offset0:42 offset1:43
	s_waitcnt lgkmcnt(0)
	v_pk_mul_f32 v[2:3], v[100:101], v[2:3]
	v_pk_mul_f32 v[18:19], v[100:101], v[18:19]
	v_pk_mul_f32 v[34:35], v[100:101], v[34:35]
	v_pk_mul_f32 v[50:51], v[100:101], v[50:51]
	v_pk_mul_f32 v[4:5], v[4:5], v[102:103]
	v_pk_mul_f32 v[20:21], v[20:21], v[102:103]
	v_pk_mul_f32 v[36:37], v[36:37], v[102:103]
	v_pk_mul_f32 v[52:53], v[52:53], v[102:103]
	v_pk_mul_f32 v[6:7], v[6:7], v[104:105]
	v_pk_mul_f32 v[22:23], v[22:23], v[104:105]
	v_pk_mul_f32 v[38:39], v[38:39], v[104:105]
	v_pk_mul_f32 v[54:55], v[54:55], v[104:105]
	v_pk_mul_f32 v[8:9], v[8:9], v[106:107]
	v_pk_mul_f32 v[24:25], v[24:25], v[106:107]
	v_pk_mul_f32 v[40:41], v[40:41], v[106:107]
	ds_read2_b32 v[100:101], v189 offset0:48 offset1:49
	v_pk_mul_f32 v[56:57], v[56:57], v[106:107]
	ds_read2_b32 v[102:103], v189 offset0:50 offset1:51
	ds_read2_b32 v[104:105], v189 offset0:56 offset1:57
	ds_read2_b32 v[106:107], v189 offset0:58 offset1:59
	s_waitcnt lgkmcnt(0)
	v_pk_mul_f32 v[10:11], v[10:11], v[100:101]
	v_pk_mul_f32 v[26:27], v[26:27], v[100:101]
	v_pk_mul_f32 v[42:43], v[42:43], v[100:101]
	v_pk_mul_f32 v[58:59], v[58:59], v[100:101]
	v_pk_mul_f32 v[12:13], v[12:13], v[102:103]
	v_pk_mul_f32 v[28:29], v[28:29], v[102:103]
	v_pk_mul_f32 v[44:45], v[44:45], v[102:103]
	v_pk_mul_f32 v[60:61], v[60:61], v[102:103]
	v_pk_mul_f32 v[14:15], v[14:15], v[104:105]
	v_pk_mul_f32 v[30:31], v[30:31], v[104:105]
	v_pk_mul_f32 v[46:47], v[46:47], v[104:105]
	v_pk_mul_f32 v[62:63], v[62:63], v[104:105]
	v_pk_mul_f32 v[16:17], v[16:17], v[106:107]
	v_pk_mul_f32 v[32:33], v[32:33], v[106:107]
	v_pk_mul_f32 v[48:49], v[48:49], v[106:107]
	v_pk_mul_f32 v[64:65], v[64:65], v[106:107]

.LBB0_1893:
	ds_read_b128 v[90:93], v198 offset:49152
	ds_read_b128 v[86:89], v197 offset:49152
	ds_read_b128 v[130:133], v197 offset:53248
	ds_read_b128 v[134:137], v198 offset:53248
	v_pk_add_f32 v[94:95], v[82:83], v[84:85]
	s_waitcnt lgkmcnt(0)
	v_mfma_f32_32x32x64_f8f6f4 v[114:129], v[86:93], v[154:161], 0
	s_nop 0
	v_exp_f32_e32 v66, v66
	v_exp_f32_e32 v67, v67
	v_exp_f32_e32 v68, v68
	v_exp_f32_e32 v69, v69
	ds_read_b128 v[86:89], v195 offset:49152
	ds_read_b128 v[90:93], v196 offset:49152
	v_mfma_f32_32x32x64_f8f6f4 v[98:113], v[130:137], v[154:161], 0
	ds_read_b128 v[130:133], v195 offset:53248
	ds_read_b128 v[134:137], v196 offset:53248
	v_exp_f32_e32 v70, v70
	v_exp_f32_e32 v71, v71
	v_exp_f32_e32 v72, v72
	v_exp_f32_e32 v73, v73
	v_pk_add_f32 v[94:95], v[94:95], v[172:173]
	s_waitcnt lgkmcnt(0)
	v_mfma_f32_32x32x64_f8f6f4 v[114:129], v[86:93], v[146:153], v[114:129]
	v_pk_add_f32 v[94:95], v[94:95], v[170:171]
	v_exp_f32_e32 v74, v74
	v_exp_f32_e32 v75, v75
	v_exp_f32_e32 v76, v76
	v_exp_f32_e32 v77, v77
	v_pk_add_f32 v[86:87], v[94:95], v[168:169]
	v_mfma_f32_32x32x64_f8f6f4 v[98:113], v[130:137], v[146:153], v[98:113]
	v_mov_b32_e32 v134, v163
	v_pk_add_f32 v[86:87], v[86:87], v[140:141]
	v_cvt_pk_fp8_f32 v134, v66, v67
	v_pk_add_f32 v[86:87], v[86:87], v[144:145]
	v_mov_b32_e32 v135, v163
	v_exp_f32_e32 v78, v78
	v_exp_f32_e32 v79, v79
	v_pk_add_f32 v[86:87], v[86:87], v[142:143]
	v_cvt_pk_fp8_f32 v135, v70, v71
	v_pk_add_f32 v[86:87], v[86:87], v[66:67]
	v_mov_b32_e32 v136, v163
	ds_read_b64_tr_b8 v[66:67], v194 offset:0
	v_pk_add_f32 v[86:87], v[68:69], v[86:87]
	v_cvt_pk_fp8_f32 v134, v68, v69 op_sel:[0,0,1]
	v_cvt_pk_fp8_f32 v136, v74, v75
	ds_read_b64_tr_b8 v[68:69], v194 offset:0x800
	v_pk_add_f32 v[86:87], v[70:71], v[86:87]
	v_mov_b32_e32 v137, v163
	ds_read_b64_tr_b8 v[70:71], v194 offset:0x1000
	v_exp_f32_e32 v80, v80
	v_exp_f32_e32 v81, v81
	v_pk_add_f32 v[86:87], v[72:73], v[86:87]
	v_mov_b32_e32 v130, v163
	v_mov_b32_e32 v131, v163
	v_cvt_pk_fp8_f32 v135, v72, v73 op_sel:[0,0,1]
	v_mov_b32_e32 v132, v163
	v_mov_b32_e32 v133, v163
	v_cvt_pk_fp8_f32 v137, v78, v79
	ds_read_b64_tr_b8 v[72:73], v194 offset:0x1800
	v_pk_add_f32 v[86:87], v[74:75], v[86:87]
	v_cvt_pk_fp8_f32 v130, v82, v83
	v_cvt_pk_fp8_f32 v131, v172, v173
	v_cvt_pk_fp8_f32 v132, v168, v169
	v_cvt_pk_fp8_f32 v133, v144, v145
	ds_read_b64_tr_b8 v[74:75], v193 offset:0
	v_pk_add_f32 v[86:87], v[76:77], v[86:87]
	v_cvt_pk_fp8_f32 v136, v76, v77 op_sel:[0,0,1]
	ds_read_b64_tr_b8 v[76:77], v193 offset:0x800
	v_pk_add_f32 v[86:87], v[78:79], v[86:87]
	ds_read_b64_tr_b8 v[78:79], v193 offset:0x1000
	v_cvt_pk_fp8_f32 v137, v80, v81 op_sel:[0,0,1]
	v_pk_add_f32 v[86:87], v[80:81], v[86:87]
	ds_read_b64_tr_b8 v[80:81], v193 offset:0x1800
	v_cvt_pk_fp8_f32 v130, v84, v85 op_sel:[0,0,1]
	v_cvt_pk_fp8_f32 v131, v170, v171 op_sel:[0,0,1]
	v_cvt_pk_fp8_f32 v132, v140, v141 op_sel:[0,0,1]
	v_cvt_pk_fp8_f32 v133, v142, v143 op_sel:[0,0,1]
	s_waitcnt lgkmcnt(4)
	v_pk_add_f32 v[138:139], v[86:87], v[86:87] op_sel:[0,1] op_sel_hi:[1,0]
	v_mfma_f32_32x32x64_f8f6f4 v[2:17], v[130:137], v[66:73], v[2:17]
	ds_read_b64_tr_b8 v[140:141], v192 offset:0
	ds_read_b64_tr_b8 v[142:143], v192 offset:0x800
	ds_read_b64_tr_b8 v[144:145], v192 offset:0x1000
	ds_read_b64_tr_b8 v[146:147], v192 offset:0x1800
	s_waitcnt lgkmcnt(4)
	s_nop 0
	v_max_f32_e32 v66, v114, v115
	v_max3_f32 v66, v66, v116, v117
	v_max3_f32 v66, v66, v118, v119
	v_max3_f32 v66, v66, v120, v121
	v_max3_f32 v66, v66, v122, v123
	v_max3_f32 v66, v66, v124, v125
	v_max3_f32 v66, v66, v126, v127
	v_max3_f32 v66, v66, v128, v129
	v_max3_f32 v66, v66, v98, v99
	v_max3_f32 v66, v66, v100, v101
	v_max3_f32 v66, v66, v102, v103
	v_max3_f32 v66, v66, v104, v105
	v_max3_f32 v66, v66, v106, v107
	v_max3_f32 v66, v66, v108, v109
	v_max3_f32 v66, v66, v110, v111
	v_max3_f32 v66, v66, v112, v113
	v_mov_b32_e32 v67, v66
	s_nop 1
	v_permlane32_swap_b32_e32 v66, v67
	v_max_f32_e32 v66, v66, v67
	v_sub_f32_e32 v67, v66, v200
	v_cmp_ge_f32_e32 vcc, s38, v67
	s_cmp_eq_u64 vcc, exec
	v_max_f32_e32 v66, v200, v66
	s_cselect_b64 vcc, -1, 0
	v_sub_f32_e32 v67, v200, v66
	v_cndmask_b32_e32 v66, v66, v200, vcc
	v_mul_f32_e32 v83, 0x3e0293ee, v67
	v_fma_f32 v82, v66, s39, 4.0
	v_mfma_f32_32x32x64_f8f6f4 v[18:33], v[130:137], v[74:81], v[18:33]
	v_mov_b32_e32 v139, v138
	v_pk_fma_f32 v[84:85], v[100:101], s[6:7], v[82:83] op_sel_hi:[1,0,0]
	ds_read_b64_tr_b8 v[100:101], v190 offset:0
	v_pk_fma_f32 v[66:67], v[114:115], s[6:7], v[82:83] op_sel_hi:[1,0,0]
	v_exp_f32_e32 v114, v83
	v_pk_fma_f32 v[86:87], v[102:103], s[6:7], v[82:83] op_sel_hi:[1,0,0]
	ds_read_b64_tr_b8 v[102:103], v190 offset:0x800
	v_pk_fma_f32 v[88:89], v[104:105], s[6:7], v[82:83] op_sel_hi:[1,0,0]
	ds_read_b64_tr_b8 v[104:105], v190 offset:0x1000
	v_pk_fma_f32 v[80:81], v[128:129], s[6:7], v[82:83] op_sel_hi:[1,0,0]
	v_pk_fma_f32 v[78:79], v[126:127], s[6:7], v[82:83] op_sel_hi:[1,0,0]
	v_pk_fma_f32 v[76:77], v[124:125], s[6:7], v[82:83] op_sel_hi:[1,0,0]
	v_pk_fma_f32 v[74:75], v[122:123], s[6:7], v[82:83] op_sel_hi:[1,0,0]
	v_pk_fma_f32 v[72:73], v[120:121], s[6:7], v[82:83] op_sel_hi:[1,0,0]
	v_pk_fma_f32 v[70:71], v[118:119], s[6:7], v[82:83] op_sel_hi:[1,0,0]
	v_pk_fma_f32 v[68:69], v[116:117], s[6:7], v[82:83] op_sel_hi:[1,0,0]
	v_pk_fma_f32 v[96:97], v[112:113], s[6:7], v[82:83] op_sel_hi:[1,0,0]
	v_pk_fma_f32 v[94:95], v[110:111], s[6:7], v[82:83] op_sel_hi:[1,0,0]
	v_pk_fma_f32 v[92:93], v[108:109], s[6:7], v[82:83] op_sel_hi:[1,0,0]
	v_pk_fma_f32 v[90:91], v[106:107], s[6:7], v[82:83] op_sel_hi:[1,0,0]
	v_pk_fma_f32 v[82:83], v[98:99], s[6:7], v[82:83] op_sel_hi:[1,0,0]
	ds_read_b64_tr_b8 v[106:107], v190 offset:0x1800
	s_waitcnt lgkmcnt(4)
	v_cndmask_b32_e64 v98, v114, 1.0, vcc
	v_mfma_f32_32x32x64_f8f6f4 v[34:49], v[130:137], v[140:147], v[34:49]
	s_waitcnt lgkmcnt(0)
	v_permlane32_swap_b32_e32 v138, v139
	v_exp_f32_e32 v66, v66
	v_exp_f32_e32 v67, v67
	v_exp_f32_e32 v68, v68
	v_exp_f32_e32 v69, v69
	v_cmp_gt_f32_e32 vcc, 1.0, v98
	v_mfma_f32_32x32x64_f8f6f4 v[50:65], v[130:137], v[100:107], v[50:65]
	s_cbranch_vccz .LBB0_1897
	s_and_saveexec_b64 s[28:29], s[2:3]
	ds_write_b32 v191, v98 offset:128
	s_or_b64 exec, exec, s[28:29]
	s_waitcnt lgkmcnt(0)
	s_nop 15
	s_nop 7
	ds_read2_b32 v[100:101], v189 offset0:32 offset1:33
	ds_read2_b32 v[102:103], v189 offset0:34 offset1:35
	ds_read2_b32 v[104:105], v189 offset0:40 offset1:41
	ds_read2_b32 v[106:107], v189 offset0:42 offset1:43
	s_waitcnt lgkmcnt(0)
	v_pk_mul_f32 v[2:3], v[100:101], v[2:3]
	v_pk_mul_f32 v[18:19], v[100:101], v[18:19]
	v_pk_mul_f32 v[34:35], v[100:101], v[34:35]
	v_pk_mul_f32 v[50:51], v[100:101], v[50:51]
	v_pk_mul_f32 v[4:5], v[4:5], v[102:103]
	v_pk_mul_f32 v[20:21], v[20:21], v[102:103]
	v_pk_mul_f32 v[36:37], v[36:37], v[102:103]
	v_pk_mul_f32 v[52:53], v[52:53], v[102:103]
	v_pk_mul_f32 v[6:7], v[6:7], v[104:105]
	v_pk_mul_f32 v[22:23], v[22:23], v[104:105]
	v_pk_mul_f32 v[38:39], v[38:39], v[104:105]
	v_pk_mul_f32 v[54:55], v[54:55], v[104:105]
	v_pk_mul_f32 v[8:9], v[8:9], v[106:107]
	v_pk_mul_f32 v[24:25], v[24:25], v[106:107]
	v_pk_mul_f32 v[40:41], v[40:41], v[106:107]
	ds_read2_b32 v[100:101], v189 offset0:48 offset1:49
	v_pk_mul_f32 v[56:57], v[56:57], v[106:107]
	ds_read2_b32 v[102:103], v189 offset0:50 offset1:51
	ds_read2_b32 v[104:105], v189 offset0:56 offset1:57
	ds_read2_b32 v[106:107], v189 offset0:58 offset1:59
	s_waitcnt lgkmcnt(0)
	v_pk_mul_f32 v[10:11], v[10:11], v[100:101]
	v_pk_mul_f32 v[26:27], v[26:27], v[100:101]
	v_pk_mul_f32 v[42:43], v[42:43], v[100:101]
	v_pk_mul_f32 v[58:59], v[58:59], v[100:101]
	v_pk_mul_f32 v[12:13], v[12:13], v[102:103]
	v_pk_mul_f32 v[28:29], v[28:29], v[102:103]
	v_pk_mul_f32 v[44:45], v[44:45], v[102:103]
	v_pk_mul_f32 v[60:61], v[60:61], v[102:103]
	v_pk_mul_f32 v[14:15], v[14:15], v[104:105]
	v_pk_mul_f32 v[30:31], v[30:31], v[104:105]
	v_pk_mul_f32 v[46:47], v[46:47], v[104:105]
	v_pk_mul_f32 v[62:63], v[62:63], v[104:105]
	v_pk_mul_f32 v[16:17], v[16:17], v[106:107]
	v_pk_mul_f32 v[32:33], v[32:33], v[106:107]
	v_pk_mul_f32 v[48:49], v[48:49], v[106:107]
	v_pk_mul_f32 v[64:65], v[64:65], v[106:107]
